# mix loop waits relaxed + attention: epilogue loads batched, QK/PV LDS reads pipelined, ticket prefetch + G3 a_ready skip when panel unchanged
# baseline (speedup 1.0000x reference)
; __device__ __forceinline__ void mix_phase(const Params& p, LAS unsigned char* lds, int G, bool dry) {
;     ...
;         for (int i = 0; i < 8; ++i) {
;             const int cid = tid + 512 * i, s = cid >> 5, c = (cid & 31) * 8;
;             const float mu = st[s], rs = st[128 + s];
;             f32x4 x0 = (f32x4){bf_lo(raw[i].x), bf_hi(raw[i].x), bf_lo(raw[i].y), bf_hi(raw[i].y)}, x1 = (f32x4){bf_lo(raw[i].z), bf_hi(raw[i].z), bf_lo(raw[i].w), bf_hi(raw[i].w)};
;             x0 = (x0 - mu) * rs * g0 + b0; x1 = (x1 - mu) * rs * g1 + b1;
;             if (smp) { float* o = p.out + O_GMV + (size_t)(row_base - MP + s) * GW + g * 256 + c; __builtin_nontemporal_store(x0, (f32x4*)o); __builtin_nontemporal_store(x1, (f32x4*)(o + 4)); }
;             u32x4 w; w.x = cvt_pk_bf16(x0[0], x0[1]); w.y = cvt_pk_bf16(x0[2], x0[3]); w.z = cvt_pk_bf16(x1[0], x1[1]); w.w = cvt_pk_bf16(x1[2], x1[3]);
;             *(LAS u32x4*)(Vl + s * MIX_VP + c) = w;
;         }
;         u32x2 ur[4][4]; float bias[4];
;         bf16_t* const gup = gu + (size_t)(row_base + 64 * wr + fr) * GW + g * 256 + 64 * wc + 4 * fq;
; #pragma unroll
;         for (int m = 0; m < 4; ++m) {
;             const int tt = 64 * wr + 16 * m + fr; bias[m] = p.bsp[g * 128 + (smp ? (tt & 31) : tt)];
; #pragma unroll
;             for (int n = 0; n < 4; ++n) ur[m][n] = __builtin_nontemporal_load((const u32x2*)(gup + (size_t)m * 16 * GW + 16 * n));
;         }
;         __syncthreads();
;         f32x4 acc[4][4];
; #pragma unroll
;         for (int m = 0; m < 4; ++m)
; #pragma unroll
;             for (int n = 0; n < 4; ++n) acc[m][n] = (f32x4){0.f, 0.f, 0.f, 0.f};
; #pragma unroll
;         for (int ks = 0; ks < 4; ++ks) {
;             bf16x8 af[4], bfr[4];
; #pragma unroll
;             for (int m = 0; m < 4; ++m) af[m] = *(const LAS bf16x8*)(Wl + (64 * wr + 16 * m + fr) * MIX_WP + 32 * ks + 8 * fq);
; #pragma unroll
;             for (int n = 0; n < 4; ++n) {
;                 const LAS bf16_t* a0 = Vl + (32 * ks + 8 * fq + (fr >> 2)) * MIX_VP + 64 * wc + 16 * n + 4 * (fr & 3);
;                 const s16x4 lo = __builtin_amdgcn_ds_read_tr16_b64_v4i16((LAS s16x4*)a0), hi = __builtin_amdgcn_ds_read_tr16_b64_v4i16((LAS s16x4*)(a0 + 4 * MIX_VP));
;                 bfr[n] = (bf16x8){lo[0], lo[1], lo[2], lo[3], hi[0], hi[1], hi[2], hi[3]};
;             }
; #pragma unroll
;             for (int m = 0; m < 4; ++m)
.LBB0_214:
	v_cvt_pk_bf16_f32 v0, v0, v1
	v_cvt_pk_bf16_f32 v1, v2, v3
	v_cvt_pk_bf16_f32 v2, v4, v5
	v_cvt_pk_bf16_f32 v3, v6, v7
	ds_write_b128 v127, v[0:3] offset:34816
	v_add_u32_e32 v0, s37, v95
	v_ashrrev_i32_e32 v1, 31, v0
	v_lshlrev_b64 v[0:1], 13, v[0:1]
	v_lshl_add_u64 v[0:1], s[0:1], 0, v[0:1]
	s_lshl_b32 s18, s34, 1
	v_lshl_add_u64 v[0:1], v[0:1], 0, s[18:19]
	v_lshl_add_u64 v[0:1], v[0:1], 0, v[82:83]
	v_mov_b32_e32 v93, v83
	s_lshl_b32 s10, s36, 7
	v_lshl_add_u64 v[34:35], v[0:1], 0, v[92:93]
	v_add_u32_e32 v0, s10, v11
	v_ashrrev_i32_e32 v1, 31, v0
	v_add_u32_e32 v2, s10, v10
	v_lshl_add_u64 v[0:1], v[0:1], 2, s[76:77]
	v_ashrrev_i32_e32 v3, 31, v2
	global_load_dwordx2 v[46:47], v[34:35], off nt
	global_load_dwordx2 v[44:45], v[34:35], off offset:32 nt
	global_load_dwordx2 v[42:43], v[34:35], off offset:64 nt
	global_load_dwordx2 v[38:39], v[34:35], off offset:96 nt
	v_lshl_add_u64 v[2:3], v[2:3], 2, s[76:77]
	global_load_dword v40, v[0:1], off
	global_load_dword v28, v[2:3], off
	v_add_co_u32_e32 v22, vcc, s40, v34
	v_add_u32_e32 v0, s10, v9
	s_nop 0
	v_addc_co_u32_e32 v23, vcc, 0, v35, vcc
	global_load_dwordx2 v[36:37], v[22:23], off nt
	global_load_dwordx2 v[32:33], v[22:23], off offset:32 nt
	global_load_dwordx2 v[30:31], v[22:23], off offset:64 nt
	global_load_dwordx2 v[26:27], v[22:23], off offset:96 nt
	v_ashrrev_i32_e32 v1, 31, v0
	v_lshl_add_u64 v[0:1], v[0:1], 2, s[76:77]
	global_load_dword v16, v[0:1], off
	v_add_co_u32_e32 v10, vcc, s41, v34
	v_add_u32_e32 v0, s10, v8
	s_nop 0
	v_addc_co_u32_e32 v11, vcc, 0, v35, vcc
	global_load_dwordx2 v[24:25], v[10:11], off nt
	global_load_dwordx2 v[20:21], v[10:11], off offset:32 nt
	global_load_dwordx2 v[18:19], v[10:11], off offset:64 nt
	global_load_dwordx2 v[14:15], v[10:11], off offset:96 nt
	v_ashrrev_i32_e32 v1, 31, v0
	v_lshl_add_u64 v[0:1], v[0:1], 2, s[76:77]
	global_load_dword v4, v[0:1], off
	v_add_co_u32_e32 v0, vcc, s42, v34
	s_waitcnt vmcnt(15)
	v_lshlrev_b32_e32 v5, 16, v46
	v_addc_co_u32_e32 v1, vcc, 0, v35, vcc
	global_load_dwordx2 v[12:13], v[0:1], off nt
	global_load_dwordx2 v[8:9], v[0:1], off offset:32 nt
	global_load_dwordx2 v[6:7], v[0:1], off offset:64 nt
	global_load_dwordx2 v[2:3], v[0:1], off offset:96 nt
	s_waitcnt lgkmcnt(0)
	s_barrier
	ds_read_b64_tr_b16 v[50:51], v116 offset:36928
	ds_read_b64_tr_b16 v[48:49], v116 offset:34816
	ds_read_b128 v[52:55], v128
	ds_read_b64_tr_b16 v[58:59], v116 offset:36960
	ds_read_b64_tr_b16 v[56:57], v116 offset:34848
	ds_read_b64_tr_b16 v[60:61], v116 offset:34880
	ds_read_b64_tr_b16 v[64:65], v116 offset:34912
	ds_read_b64_tr_b16 v[62:63], v116 offset:36992
	ds_read_b64_tr_b16 v[66:67], v116 offset:37024
	ds_read_b128 v[68:71], v128 offset:64
	ds_read_b128 v[136:139], v128 offset:4352
	ds_read_b128 v[140:143], v128 offset:4416
	ds_read_b128 v[156:159], v128 offset:8704
	ds_read_b128 v[160:163], v128 offset:8768
	ds_read_b128 v[176:179], v128 offset:13056
	ds_read_b128 v[180:183], v128 offset:13120
	s_waitcnt lgkmcnt(13)
	v_mfma_f32_16x16x32_bf16 v[72:75], v[48:51], v[52:55], 0
	ds_read_b64_tr_b16 v[184:185], v116 offset:51712
	ds_read_b64_tr_b16 v[186:187], v116 offset:53824
	v_and_b32_e32 v17, 0xffff0000, v46
	s_waitcnt lgkmcnt(13)
	v_mfma_f32_16x16x32_bf16 v[76:79], v[56:59], v[52:55], 0
	s_waitcnt lgkmcnt(10)
	v_mfma_f32_16x16x32_bf16 v[132:135], v[60:63], v[52:55], 0
	s_waitcnt lgkmcnt(9)
	v_mfma_f32_16x16x32_bf16 v[52:55], v[64:67], v[52:55], 0
	s_waitcnt lgkmcnt(7)
	v_mfma_f32_16x16x32_bf16 v[144:147], v[48:51], v[136:139], 0
	v_mfma_f32_16x16x32_bf16 v[148:151], v[56:59], v[136:139], 0
	v_mfma_f32_16x16x32_bf16 v[152:155], v[60:63], v[136:139], 0
	v_mfma_f32_16x16x32_bf16 v[136:139], v[64:67], v[136:139], 0
	s_waitcnt lgkmcnt(5)
	v_mfma_f32_16x16x32_bf16 v[164:167], v[48:51], v[156:159], 0
	v_mfma_f32_16x16x32_bf16 v[168:171], v[56:59], v[156:159], 0
	v_mfma_f32_16x16x32_bf16 v[172:175], v[60:63], v[156:159], 0
	v_mfma_f32_16x16x32_bf16 v[156:159], v[64:67], v[156:159], 0
	s_waitcnt lgkmcnt(3)
	v_mfma_f32_16x16x32_bf16 v[48:51], v[48:51], v[176:179], 0
	v_mfma_f32_16x16x32_bf16 v[56:59], v[56:59], v[176:179], 0
	v_mfma_f32_16x16x32_bf16 v[60:63], v[60:63], v[176:179], 0
	v_mfma_f32_16x16x32_bf16 v[64:67], v[64:67], v[176:179], 0
	ds_read_b64_tr_b16 v[178:179], v116 offset:53856
	ds_read_b64_tr_b16 v[176:177], v116 offset:51744
	ds_read_b64_tr_b16 v[188:189], v116 offset:51776
	ds_read_b64_tr_b16 v[196:197], v116 offset:51808
	ds_read_b64_tr_b16 v[190:191], v116 offset:53888
	ds_read_b64_tr_b16 v[198:199], v116 offset:53920
	s_waitcnt lgkmcnt(6)
	v_mfma_f32_16x16x32_bf16 v[72:75], v[184:187], v[68:71], v[72:75]
	s_waitcnt lgkmcnt(4)
	v_mfma_f32_16x16x32_bf16 v[76:79], v[176:179], v[68:71], v[76:79]
	s_waitcnt lgkmcnt(1)
	v_mfma_f32_16x16x32_bf16 v[132:135], v[188:191], v[68:71], v[132:135]
	s_waitcnt lgkmcnt(0)
; __device__ __forceinline__ unsigned cvt_pk_bf16(float lo, float hi) { unsigned r; asm volatile("v_cvt_pk_bf16_f32 %0, %1, %2" : "=v"(r) : "v"(lo), "v"(hi)); return r; }
; __device__ __forceinline__ float bf_lo(unsigned w) { return __uint_as_float(w << 16); }
; __device__ __forceinline__ float bf_hi(unsigned w) { return __uint_as_float(w & 0xffff0000u); }
; __device__ __forceinline__ void mix_phase(const Params& p, LAS unsigned char* lds, int G, bool dry) {
;     ...
; #pragma unroll
;             for (int m = 0; m < 4; ++m)
; #pragma unroll
;                 for (int n = 0; n < 4; ++n) acc[m][n] = __builtin_amdgcn_mfma_f32_16x16x32_bf16(bfr[n], af[m], acc[m][n], 0, 0, 0);
;         }
; #pragma unroll
;         for (int m = 0; m < 4; ++m) {
; #pragma unroll
;             for (int n = 0; n < 4; ++n) {
;                 const f32x4 a = acc[m][n] + bias[m]; const u32x2 u2 = ur[m][n];
;                 u32x2 w; w.x = cvt_pk_bf16(bf_lo(u2.x) * a[0], bf_hi(u2.x) * a[1]); w.y = cvt_pk_bf16(bf_lo(u2.y) * a[2], bf_hi(u2.y) * a[3]);
;                 if (!dry) *(u32x2*)(gup + (size_t)m * 16 * GW + 16 * n) = w;
;             }
	v_mfma_f32_16x16x32_bf16 v[52:55], v[196:199], v[68:71], v[52:55]
	v_mfma_f32_16x16x32_bf16 v[68:71], v[184:187], v[140:143], v[144:147]
	v_mfma_f32_16x16x32_bf16 v[144:147], v[176:179], v[140:143], v[148:151]
	v_mfma_f32_16x16x32_bf16 v[148:151], v[188:191], v[140:143], v[152:155]
	v_mfma_f32_16x16x32_bf16 v[136:139], v[196:199], v[140:143], v[136:139]
	v_mfma_f32_16x16x32_bf16 v[140:143], v[184:187], v[160:163], v[164:167]
	v_mfma_f32_16x16x32_bf16 v[152:155], v[176:179], v[160:163], v[168:171]
	v_mfma_f32_16x16x32_bf16 v[164:167], v[188:191], v[160:163], v[172:175]
	v_mfma_f32_16x16x32_bf16 v[156:159], v[196:199], v[160:163], v[156:159]
	ds_read_b128 v[160:163], v128 offset:128
	ds_read_b64_tr_b16 v[170:171], v117 offset:35904
	v_mfma_f32_16x16x32_bf16 v[48:51], v[184:187], v[180:183], v[48:51]
	v_mfma_f32_16x16x32_bf16 v[56:59], v[176:179], v[180:183], v[56:59]
	ds_read_b64_tr_b16 v[168:169], v117 offset:33792
	ds_read_b64_tr_b16 v[172:173], v117 offset:33824
	ds_read_b64_tr_b16 v[176:177], v117 offset:33856
	ds_read_b64_tr_b16 v[184:185], v117 offset:33888
	v_mfma_f32_16x16x32_bf16 v[60:63], v[188:191], v[180:183], v[60:63]
	v_mfma_f32_16x16x32_bf16 v[64:67], v[196:199], v[180:183], v[64:67]
	ds_read_b64_tr_b16 v[174:175], v117 offset:35936
	ds_read_b64_tr_b16 v[178:179], v117 offset:35968
	ds_read_b64_tr_b16 v[186:187], v117 offset:36000
	ds_read_b128 v[180:183], v128 offset:192
	ds_read_b128 v[188:191], v128 offset:4480
	ds_read_b128 v[196:199], v128 offset:4544
	ds_read_b128 v[200:203], v128 offset:8832
	ds_read_b128 v[204:207], v128 offset:8896
	ds_read_b128 v[208:211], v128 offset:13184
	ds_read_b128 v[212:215], v128 offset:13248
	ds_read_b64_tr_b16 v[216:217], v117 offset:50688
	ds_read_b64_tr_b16 v[218:219], v117 offset:52800
	s_waitcnt lgkmcnt(14)
	v_mfma_f32_16x16x32_bf16 v[72:75], v[168:171], v[160:163], v[72:75]
	ds_read_b64_tr_b16 v[220:221], v117 offset:50720
	ds_read_b64_tr_b16 v[224:225], v117 offset:50752
	ds_read_b64_tr_b16 v[228:229], v117 offset:50784
	ds_read_b64_tr_b16 v[222:223], v117 offset:52832
	ds_read_b64_tr_b16 v[226:227], v117 offset:52864
	ds_read_b64_tr_b16 v[230:231], v117 offset:52896
	s_waitcnt lgkmcnt(14)
	v_mfma_f32_16x16x32_bf16 v[76:79], v[172:175], v[160:163], v[76:79]
	s_waitcnt lgkmcnt(6)
	v_mfma_f32_16x16x32_bf16 v[72:75], v[216:219], v[180:183], v[72:75]
	s_waitcnt lgkmcnt(2)
	v_mfma_f32_16x16x32_bf16 v[76:79], v[220:223], v[180:183], v[76:79]
	v_mfma_f32_16x16x32_bf16 v[132:135], v[176:179], v[160:163], v[132:135]
	s_waitcnt vmcnt(15)
	s_nop 3
	v_pk_add_f32 v[72:73], v[40:41], v[72:73] op_sel_hi:[0,1]
	v_mul_f32_e32 v5, v72, v5
	v_mul_f32_e32 v17, v73, v17
	v_mfma_f32_16x16x32_bf16 v[52:55], v[184:187], v[160:163], v[52:55]
	v_add_f32_e64 v160, v40, v74
	v_add_f32_e64 v161, v40, v75
	v_cvt_pk_bf16_f32 v46, v5, v17
	v_lshlrev_b32_e32 v5, 16, v47
	v_and_b32_e32 v17, 0xffff0000, v47
	v_mul_f32_e32 v5, v160, v5
	v_mul_f32_e32 v17, v161, v17
	v_mfma_f32_16x16x32_bf16 v[72:75], v[172:175], v[188:191], v[144:147]
	v_cvt_pk_bf16_f32 v47, v5, v17
	v_lshlrev_b32_e32 v5, 16, v44
	v_and_b32_e32 v17, 0xffff0000, v44
	v_mfma_f32_16x16x32_bf16 v[144:147], v[176:179], v[188:191], v[148:151]
	global_store_dwordx2 v[34:35], v[46:47], off
	v_pk_add_f32 v[46:47], v[40:41], v[78:79] op_sel_hi:[0,1]
	s_nop 0
	v_pk_add_f32 v[148:149], v[40:41], v[76:77] op_sel_hi:[0,1]
	v_mul_f32_e32 v5, v148, v5
	v_mul_f32_e32 v17, v149, v17
	v_cvt_pk_bf16_f32 v148, v5, v17
	v_lshlrev_b32_e32 v5, 16, v45
	v_and_b32_e32 v17, 0xffff0000, v45
	v_mul_f32_e32 v5, v46, v5
	v_mul_f32_e32 v17, v47, v17
	s_waitcnt lgkmcnt(1)
	v_mfma_f32_16x16x32_bf16 v[44:47], v[224:227], v[180:183], v[132:135]
	v_cvt_pk_bf16_f32 v149, v5, v17
	v_lshlrev_b32_e32 v5, 16, v42
	v_and_b32_e32 v17, 0xffff0000, v42
	v_mfma_f32_16x16x32_bf16 v[68:71], v[168:171], v[188:191], v[68:71]
	global_store_dwordx2 v[34:35], v[148:149], off offset:32
	s_nop 3
	v_pk_add_f32 v[150:151], v[40:41], v[44:45] op_sel_hi:[0,1]
	v_mul_f32_e32 v5, v150, v5
	s_waitcnt lgkmcnt(0)
	v_mfma_f32_16x16x32_bf16 v[52:55], v[228:231], v[180:183], v[52:55]
	v_mul_f32_e32 v17, v151, v17
	v_pk_add_f32 v[148:149], v[40:41], v[46:47] op_sel_hi:[0,1]
	v_cvt_pk_bf16_f32 v42, v5, v17
	v_lshlrev_b32_e32 v5, 16, v43
	v_and_b32_e32 v17, 0xffff0000, v43
	v_mul_f32_e32 v5, v148, v5
	v_mul_f32_e32 v17, v149, v17
	v_cvt_pk_bf16_f32 v43, v5, v17
	global_store_dwordx2 v[34:35], v[42:43], off offset:64
	s_nop 0
	v_pk_add_f32 v[148:149], v[40:41], v[54:55] op_sel_hi:[0,1]
	v_pk_add_f32 v[52:53], v[40:41], v[52:53] op_sel_hi:[0,1]
	v_lshlrev_b32_e32 v5, 16, v38
	v_mfma_f32_16x16x32_bf16 v[40:43], v[176:179], v[208:211], v[60:63]
	v_and_b32_e32 v17, 0xffff0000, v38
	v_mul_f32_e32 v5, v52, v5
	v_mul_f32_e32 v17, v53, v17
	v_mfma_f32_16x16x32_bf16 v[60:63], v[216:219], v[196:199], v[68:71]
	v_cvt_pk_bf16_f32 v38, v5, v17
	v_lshlrev_b32_e32 v5, 16, v39
	v_and_b32_e32 v17, 0xffff0000, v39
	v_mul_f32_e32 v5, v148, v5
	v_mul_f32_e32 v17, v149, v17
	v_cvt_pk_bf16_f32 v39, v5, v17
	v_mfma_f32_16x16x32_bf16 v[52:55], v[184:187], v[208:211], v[64:67]
	global_store_dwordx2 v[34:35], v[38:39], off offset:96
	s_waitcnt vmcnt(18)
	s_nop 0
	v_pk_add_f32 v[38:39], v[28:29], v[60:61] op_sel_hi:[0,1]
	s_waitcnt vmcnt(17)
	v_lshlrev_b32_e32 v5, 16, v36
	v_mfma_f32_16x16x32_bf16 v[64:67], v[220:223], v[196:199], v[72:75]
	v_and_b32_e32 v17, 0xffff0000, v36
	v_mul_f32_e32 v5, v38, v5
	v_mul_f32_e32 v17, v39, v17
	v_pk_add_f32 v[34:35], v[28:29], v[62:63] op_sel_hi:[0,1]
	v_cvt_pk_bf16_f32 v38, v5, v17
	v_lshlrev_b32_e32 v5, 16, v37
	v_and_b32_e32 v17, 0xffff0000, v37
	v_mul_f32_e32 v5, v34, v5
	v_mul_f32_e32 v17, v35, v17
	v_mfma_f32_16x16x32_bf16 v[76:79], v[184:187], v[188:191], v[136:139]
	v_cvt_pk_bf16_f32 v39, v5, v17
	v_add_f32_e64 v64, v28, v64
	v_add_f32_e64 v65, v28, v65
	s_waitcnt vmcnt(16)
; __device__ __forceinline__ unsigned cvt_pk_bf16(float lo, float hi) { unsigned r; asm volatile("v_cvt_pk_bf16_f32 %0, %1, %2" : "=v"(r) : "v"(lo), "v"(hi)); return r; }
; __device__ __forceinline__ float bf_lo(unsigned w) { return __uint_as_float(w << 16); }
; __device__ __forceinline__ float bf_hi(unsigned w) { return __uint_as_float(w & 0xffff0000u); }
; __device__ __forceinline__ void mix_phase(const Params& p, LAS unsigned char* lds, int G, bool dry) {
;     ...
; #pragma unroll
;         for (int m = 0; m < 4; ++m) {
; #pragma unroll
;             for (int n = 0; n < 4; ++n) {
;                 const f32x4 a = acc[m][n] + bias[m]; const u32x2 u2 = ur[m][n];
;                 u32x2 w; w.x = cvt_pk_bf16(bf_lo(u2.x) * a[0], bf_hi(u2.x) * a[1]); w.y = cvt_pk_bf16(bf_lo(u2.y) * a[2], bf_hi(u2.y) * a[3]);
;                 if (!dry) *(u32x2*)(gup + (size_t)m * 16 * GW + 16 * n) = w;
;             }
;         }
;         if (tid == 0) misc[0] = nticket;
	v_lshlrev_b32_e32 v5, 16, v32
	v_mfma_f32_16x16x32_bf16 v[60:63], v[224:227], v[196:199], v[144:147]
	v_and_b32_e32 v17, 0xffff0000, v32
	v_mul_f32_e32 v5, v64, v5
	v_mul_f32_e32 v17, v65, v17
	global_store_dwordx2 v[22:23], v[38:39], off
	v_pk_add_f32 v[38:39], v[28:29], v[66:67] op_sel_hi:[0,1]
	v_cvt_pk_bf16_f32 v32, v5, v17
	v_lshlrev_b32_e32 v5, 16, v33
	v_and_b32_e32 v17, 0xffff0000, v33
	v_mul_f32_e32 v5, v38, v5
	v_mul_f32_e32 v17, v39, v17
	v_mfma_f32_16x16x32_bf16 v[136:139], v[168:171], v[200:203], v[140:143]
	v_cvt_pk_bf16_f32 v33, v5, v17
	s_waitcnt vmcnt(16)
	v_lshlrev_b32_e32 v5, 16, v30
	v_and_b32_e32 v17, 0xffff0000, v30
	v_mfma_f32_16x16x32_bf16 v[68:71], v[228:231], v[196:199], v[76:79]
	global_store_dwordx2 v[22:23], v[32:33], off offset:32
	v_pk_add_f32 v[32:33], v[28:29], v[62:63] op_sel_hi:[0,1]
	v_mfma_f32_16x16x32_bf16 v[38:41], v[224:227], v[212:215], v[40:43]
	s_nop 2
	v_add_f32_e64 v42, v28, v60
	v_add_f32_e64 v43, v28, v61
	v_mul_f32_e32 v5, v42, v5
	v_mul_f32_e32 v17, v43, v17
	v_cvt_pk_bf16_f32 v30, v5, v17
	v_lshlrev_b32_e32 v5, 16, v31
	v_and_b32_e32 v17, 0xffff0000, v31
	v_mul_f32_e32 v5, v32, v5
	v_mul_f32_e32 v17, v33, v17
	v_cvt_pk_bf16_f32 v31, v5, v17
	v_mfma_f32_16x16x32_bf16 v[140:143], v[172:175], v[200:203], v[152:155]
	global_store_dwordx2 v[22:23], v[30:31], off offset:64
	v_pk_add_f32 v[30:31], v[28:29], v[70:71] op_sel_hi:[0,1]
	v_pk_add_f32 v[28:29], v[28:29], v[68:69] op_sel_hi:[0,1]
	v_mfma_f32_16x16x32_bf16 v[72:75], v[216:219], v[204:207], v[136:139]
	s_waitcnt vmcnt(17)
	v_lshlrev_b32_e32 v5, 16, v26
	v_and_b32_e32 v17, 0xffff0000, v26
	v_mul_f32_e32 v5, v28, v5
	v_mul_f32_e32 v17, v29, v17
	v_cvt_pk_bf16_f32 v26, v5, v17
	v_lshlrev_b32_e32 v5, 16, v27
	v_and_b32_e32 v17, 0xffff0000, v27
	v_mul_f32_e32 v5, v30, v5
	v_mul_f32_e32 v17, v31, v17
	v_cvt_pk_bf16_f32 v27, v5, v17
	v_mfma_f32_16x16x32_bf16 v[132:135], v[176:179], v[200:203], v[164:167]
	global_store_dwordx2 v[22:23], v[26:27], off offset:96
	s_waitcnt vmcnt(17)
	v_pk_add_f32 v[22:23], v[16:17], v[74:75] op_sel_hi:[0,1]
	v_pk_add_f32 v[26:27], v[16:17], v[72:73] op_sel_hi:[0,1]
	v_mfma_f32_16x16x32_bf16 v[34:37], v[220:223], v[204:207], v[140:143]
	s_waitcnt vmcnt(16)
	v_lshlrev_b32_e32 v5, 16, v24
	v_and_b32_e32 v17, 0xffff0000, v24
	v_mul_f32_e32 v5, v26, v5
	v_mul_f32_e32 v17, v27, v17
	v_cvt_pk_bf16_f32 v24, v5, v17
	v_lshlrev_b32_e32 v5, 16, v25
	v_and_b32_e32 v17, 0xffff0000, v25
	v_mul_f32_e32 v5, v22, v5
	v_mul_f32_e32 v17, v23, v17
	v_cvt_pk_bf16_f32 v25, v5, v17
	v_mfma_f32_16x16x32_bf16 v[44:47], v[184:187], v[200:203], v[156:159]
	global_store_dwordx2 v[10:11], v[24:25], off
	v_pk_add_f32 v[22:23], v[16:17], v[36:37] op_sel_hi:[0,1]
	v_pk_add_f32 v[24:25], v[16:17], v[34:35] op_sel_hi:[0,1]
	v_mfma_f32_16x16x32_bf16 v[76:79], v[224:227], v[204:207], v[132:135]
	s_waitcnt vmcnt(16)
	v_lshlrev_b32_e32 v5, 16, v20
	v_and_b32_e32 v17, 0xffff0000, v20
	v_mul_f32_e32 v5, v24, v5
	v_mul_f32_e32 v17, v25, v17
	v_cvt_pk_bf16_f32 v20, v5, v17
	v_lshlrev_b32_e32 v5, 16, v21
	v_and_b32_e32 v17, 0xffff0000, v21
	v_mul_f32_e32 v5, v22, v5
	v_mul_f32_e32 v17, v23, v17
	v_cvt_pk_bf16_f32 v21, v5, v17
	v_mfma_f32_16x16x32_bf16 v[44:47], v[228:231], v[204:207], v[44:47]
	global_store_dwordx2 v[10:11], v[20:21], off offset:32
	v_pk_add_f32 v[20:21], v[16:17], v[78:79] op_sel_hi:[0,1]
	v_pk_add_f32 v[22:23], v[16:17], v[76:77] op_sel_hi:[0,1]
	s_waitcnt vmcnt(16)
	v_lshlrev_b32_e32 v5, 16, v18
	v_and_b32_e32 v17, 0xffff0000, v18
	v_mfma_f32_16x16x32_bf16 v[48:51], v[168:171], v[208:211], v[48:51]
	v_mul_f32_e32 v5, v22, v5
	v_mul_f32_e32 v17, v23, v17
	v_cvt_pk_bf16_f32 v18, v5, v17
	v_lshlrev_b32_e32 v5, 16, v19
	v_and_b32_e32 v17, 0xffff0000, v19
	v_mul_f32_e32 v5, v20, v5
	v_mul_f32_e32 v17, v21, v17
	v_cvt_pk_bf16_f32 v19, v5, v17
	global_store_dwordx2 v[10:11], v[18:19], off offset:64
	v_pk_add_f32 v[18:19], v[16:17], v[46:47] op_sel_hi:[0,1]
	v_pk_add_f32 v[16:17], v[16:17], v[44:45] op_sel_hi:[0,1]
	s_waitcnt vmcnt(16)
	v_lshlrev_b32_e32 v5, 16, v14
	v_and_b32_e32 v14, 0xffff0000, v14
	v_mfma_f32_16x16x32_bf16 v[48:51], v[216:219], v[212:215], v[48:51]
	v_mul_f32_e32 v5, v16, v5
	v_mul_f32_e32 v14, v17, v14
	v_cvt_pk_bf16_f32 v14, v5, v14
	v_mfma_f32_16x16x32_bf16 v[56:59], v[172:175], v[208:211], v[56:59]
	v_lshlrev_b32_e32 v5, 16, v15
	v_and_b32_e32 v15, 0xffff0000, v15
	v_mul_f32_e32 v15, v19, v15
	v_mul_f32_e32 v5, v18, v5
	v_cvt_pk_bf16_f32 v15, v5, v15
	global_store_dwordx2 v[10:11], v[14:15], off offset:96
	s_waitcnt vmcnt(16)
	v_pk_add_f32 v[10:11], v[4:5], v[50:51] op_sel_hi:[0,1]
	v_pk_add_f32 v[14:15], v[4:5], v[48:49] op_sel_hi:[0,1]
	s_waitcnt vmcnt(15)
	v_lshlrev_b32_e32 v5, 16, v12
	v_and_b32_e32 v12, 0xffff0000, v12
	v_mfma_f32_16x16x32_bf16 v[56:59], v[220:223], v[212:215], v[56:59]
	v_mul_f32_e32 v5, v14, v5
	v_mul_f32_e32 v12, v15, v12
	v_cvt_pk_bf16_f32 v12, v5, v12
	v_lshlrev_b32_e32 v5, 16, v13
	v_mul_f32_e32 v5, v10, v5
	v_and_b32_e32 v10, 0xffff0000, v13
	v_mul_f32_e32 v10, v11, v10
	v_cvt_pk_bf16_f32 v13, v5, v10
	global_store_dwordx2 v[0:1], v[12:13], off
	s_nop 0
	v_pk_add_f32 v[10:11], v[4:5], v[58:59] op_sel_hi:[0,1]
	v_pk_add_f32 v[12:13], v[4:5], v[56:57] op_sel_hi:[0,1]
	s_waitcnt vmcnt(15)
	v_lshlrev_b32_e32 v5, 16, v8
	v_and_b32_e32 v8, 0xffff0000, v8
	v_mul_f32_e32 v5, v12, v5
	v_mul_f32_e32 v8, v13, v8
	v_cvt_pk_bf16_f32 v8, v5, v8
	v_lshlrev_b32_e32 v5, 16, v9
	v_and_b32_e32 v9, 0xffff0000, v9
	v_mul_f32_e32 v9, v11, v9
	v_mul_f32_e32 v5, v10, v5
	v_cvt_pk_bf16_f32 v9, v5, v9
	global_store_dwordx2 v[0:1], v[8:9], off offset:32
	v_pk_add_f32 v[8:9], v[4:5], v[40:41] op_sel_hi:[0,1]
	v_pk_add_f32 v[10:11], v[4:5], v[38:39] op_sel_hi:[0,1]
	s_waitcnt vmcnt(15)
	v_lshlrev_b32_e32 v5, 16, v6
	v_and_b32_e32 v6, 0xffff0000, v6
	v_mfma_f32_16x16x32_bf16 v[52:55], v[228:231], v[212:215], v[52:55]
	v_mul_f32_e32 v5, v10, v5
	v_mul_f32_e32 v6, v11, v6
	v_cvt_pk_bf16_f32 v6, v5, v6
	v_lshlrev_b32_e32 v5, 16, v7
	v_and_b32_e32 v7, 0xffff0000, v7
	v_mul_f32_e32 v7, v9, v7
	v_mul_f32_e32 v5, v8, v5
	v_cvt_pk_bf16_f32 v7, v5, v7
	global_store_dwordx2 v[0:1], v[6:7], off offset:64
	s_nop 0
	v_pk_add_f32 v[6:7], v[4:5], v[54:55] op_sel_hi:[0,1]
	v_pk_add_f32 v[4:5], v[4:5], v[52:53] op_sel_hi:[0,1]
	s_waitcnt vmcnt(15)
	v_lshlrev_b32_e32 v8, 16, v2
	v_and_b32_e32 v2, 0xffff0000, v2
	v_mul_f32_e32 v4, v4, v8
	v_mul_f32_e32 v2, v5, v2
	v_cvt_pk_bf16_f32 v2, v4, v2
	v_lshlrev_b32_e32 v4, 16, v3
	v_and_b32_e32 v3, 0xffff0000, v3
	v_mul_f32_e32 v3, v7, v3
	v_mul_f32_e32 v4, v6, v4
	v_cvt_pk_bf16_f32 v3, v4, v3
	global_store_dwordx2 v[0:1], v[2:3], off offset:96
	s_and_saveexec_b64 s[10:11], s[12:13]
	s_xor_b64 s[10:11], exec, s[10:11]
	s_cbranch_execz .LBB0_157
	v_mov_b32_e32 v0, s33
	ds_write_b32 v0, v235
	s_branch .LBB0_157
; __device__ __forceinline__ unsigned xb_ld(unsigned* p)              { return __hip_atomic_load(p, __ATOMIC_RELAXED, __HIP_MEMORY_SCOPE_AGENT); }
; __device__ __forceinline__ void xcd_barrier_complete(unsigned* bar, unsigned x, unsigned& nloc, unsigned& nx) {
;     const unsigned G = gridDim.x * gridDim.y * gridDim.z;
;     unsigned sum, cnt, mine, sp = 0u;
;     for (;;) {
;         sum = 0u; cnt = 0u; mine = 0u;
; #pragma unroll
;         for (unsigned j = 0; j < 16; ++j) { const unsigned c = xb_ld(&bar[XB_XCNT(j)]); sum += c; cnt += (c > 0u) ? 1u : 0u; mine = (j == x) ? c : mine; }
; __device__ __forceinline__ void xcd_barrier(const XcdBarrier& b) {
;     asm volatile("s_waitcnt vmcnt(0)" ::: "memory");
;     __syncthreads();
;     if (threadIdx.x == 0) {
;         unsigned* bar = b.bar;
;         __builtin_amdgcn_s_waitcnt(0);
;         unsigned nloc = b.st[0], nx = b.st[1];
;         if (nloc == 0u) { xcd_barrier_complete(bar, b.x, nloc, nx); b.st[0] = nloc; b.st[1] = nx; }
.LBB0_216:
	s_waitcnt vmcnt(0)
	s_waitcnt lgkmcnt(0)
	s_barrier
	s_mov_b64 s[2:3], exec
	v_readlane_b32 s4, v234, 22
	v_readlane_b32 s5, v234, 23
	s_and_b64 s[4:5], s[2:3], s[4:5]
	s_mov_b64 exec, s[4:5]
	s_cbranch_execz .LBB0_268
	s_add_i32 s4, 0, 0x20800
	v_mov_b32_e32 v0, s4
	s_waitcnt vmcnt(0) expcnt(0) lgkmcnt(0)
	ds_read_b32 v2, v0
	s_add_i32 s4, 0, 0x20804
	v_mov_b32_e32 v0, s4
	ds_read_b32 v0, v0
	s_waitcnt lgkmcnt(1)
	v_cmp_ne_u32_e32 vcc, 0, v2
	s_cbranch_vccnz .LBB0_232
	v_readlane_b32 s4, v234, 1
	v_readlane_b32 s5, v234, 2
	v_readlane_b32 s6, v234, 0
	s_mul_i32 s33, s5, s6
	s_mul_i32 s33, s33, s4
	s_add_u32 s4, s86, 0x1200
	s_addc_u32 s5, s87, 0
	s_add_u32 s6, s86, 0x1400
	s_addc_u32 s7, s87, 0
	s_add_u32 s8, s86, 0x1500
	s_addc_u32 s9, s87, 0
	s_add_u32 s10, s86, 0x1600
	s_addc_u32 s11, s87, 0
	s_add_u32 s12, s86, 0x1700
	s_addc_u32 s13, s87, 0
	s_add_u32 s16, s86, 0x1800
	s_addc_u32 s17, s87, 0
	s_add_u32 s18, s86, 0x1900
	s_addc_u32 s19, s87, 0
	s_add_u32 s26, s86, 0x1a00
	s_addc_u32 s27, s87, 0
	s_add_u32 s28, s86, 0x1b00
	s_addc_u32 s29, s87, 0
	s_add_u32 s30, s86, 0x1c00
	s_addc_u32 s31, s87, 0
	s_add_u32 s34, s86, 0x1d00
	s_addc_u32 s35, s87, 0
	s_add_u32 s36, s86, 0x1e00
	s_addc_u32 s37, s87, 0
	s_add_u32 s38, s86, 0x1f00
	s_addc_u32 s39, s87, 0
	s_add_u32 s40, s86, 0x2000
	s_addc_u32 s41, s87, 0
	s_add_u32 s42, s86, 0x2100
	s_addc_u32 s43, s87, 0
	s_add_u32 s44, s86, 0x2200
	s_addc_u32 s45, s87, 0
	s_add_u32 s46, s86, 0x2300
	s_addc_u32 s47, s87, 0
	s_mov_b32 s54, 1
	v_mov_b32_e32 v16, 0
	s_branch .LBB0_220

;     __device__ __forceinline__ void a_ready(const Unit& u) const {
;         if (threadIdx.x < 64) panel_wait_wave0(cnt, u.pm, 8u);
;         asm volatile("" ::: "memory"); __builtin_amdgcn_s_barrier(); asm volatile("" ::: "memory");
;     }
; template <class Epi, class Sched, bool ALIGN_EPI = true>
; __device__ __forceinline__ void gemm_phase(LAS unsigned char* lds, const Gemm g, const Sched& S, const Epi& E) {
;     ...
;             const char* a2 = last ? nA : cA + (size_t)(t + 2) * kstep; const char* b2 = last ? nB : cB + (size_t)(t + 2) * kstep;
;             const char* a3 = a2 + kstep; const char* b3 = b2 + kstep;
;             if (last && has_next) S.a_ready(nxt);
.LBB0_413:
	s_cmp_eq_u32 s16, 30
	s_cselect_b64 s[6:7], -1, 0
	s_and_b64 s[8:9], s[66:67], s[6:7]
	s_andn2_b64 vcc, exec, s[8:9]
	s_cbranch_vccnz .LBB0_425
	s_cmp_eq_u32 s60, s92
	s_cbranch_scc1 .LBB0_425
	s_and_saveexec_b64 s[8:9], s[18:19]
	s_cbranch_execz .LBB0_424
	s_mov_b32 s17, 0x400001
	s_branch .LBB0_417

; #define LAS __attribute__((address_space(3)))
; __device__ __forceinline__ void attn_phase(const Params& p, LAS unsigned char* lds, int cidx) {
;     int tid_ = threadIdx.x; asm volatile("" : "+v"(tid_)); const int tid = tid_, wid = __builtin_amdgcn_readfirstlane(tid >> 6), lane = tid & 63, fr = lane & 15, fq = lane >> 4;
;     const bf16_t* qb = (const bf16_t*)(p.ws + WS_RB) + 2 * SZ_D; const bf16_t* kb = qb + SZ_D; const bf16_t* vb = qb + 2 * SZ_D; const bf16_t* sz1 = qb + 3 * SZ_D; bf16_t* y1 = (bf16_t*)(p.ws + WS_W1T);
;     unsigned* ctr = (unsigned*)(p.ws + WS_CTL) + cidx; unsigned* pcnt = (unsigned*)(p.ws + WS_CTL) + 8192; unsigned* g3cnt = (unsigned*)(p.ws + WS_CTL) + 20480;
;     unsigned long long pseen = 0ull;
;     ...
;     LAS bf16_t* Kl = (LAS bf16_t*)(lds + AT_K_OFF); LAS bf16_t* Vl = (LAS bf16_t*)(lds + AT_V_OFF); volatile LAS int* misc = (volatile LAS int*)(lds + AT_MISC_OFF);
;     int prev_pm = -1, cur_pm = -1;
;     for (;;) {
;         __syncthreads();
;         if (tid == 0) misc[0] = (int)atomicAdd(ctr, 1u);
;         __syncthreads();
;         const int item = misc[0];
;         if (item >= AT_ITEMS) break;
;         prev_pm = cur_pm;
;         const bool smp = item < 128;
;         int b, h, x, kt_hi, qrow0, tpos0; size_t krow0;
;         if (!smp) { const int it = item - 128; x = it >> 6; const int bh = it & 63; b = bh >> 4; h = bh & 15; kt_hi = 4 * x + 3; qrow0 = b * 2048 + x * 256 + 32 * wid; tpos0 = x * 256 + 32 * wid; krow0 = (size_t)b * 2048; cur_pm = b * 8 + x; }
;         else { x = 0; const int bh = item; b = bh >> 4; h = bh & 15; kt_hi = 16; qrow0 = MP + b * 32; tpos0 = 1024; krow0 = 0; cur_pm = 32; }
;         const bool active = !smp || wid == 0;
;         AT_ENSURE(cur_pm);
;         bf16x8 qf[2][4];
; #pragma unroll
;         for (int mt = 0; mt < 2; ++mt)
; #pragma unroll
;             for (int kk = 0; kk < 4; ++kk) qf[mt][kk] = __builtin_nontemporal_load((const bf16x8*)(qb + (size_t)(qrow0 + 16 * mt + fr) * DM + h * 128 + 32 * kk + 8 * fq));
;         f32x4 o[2][8];
; #pragma unroll
;         for (int mt = 0; mt < 2; ++mt)
; #pragma unroll
;             for (int dt = 0; dt < 8; ++dt) o[mt][dt] = (f32x4){0.f, 0.f, 0.f, 0.f};
;         float C[2] = {0.f, 0.f};
;         bool wdone = !active;
;         if (lane == 0) misc[8 + wid] = wdone ? 1 : 0;
.LBB0_601:
	s_cmp_lt_u32 s94, 8
	s_cselect_b64 s[2:3], -1, 0
	s_and_b64 s[2:3], s[2:3], s[28:29]
	s_and_b64 vcc, exec, s[2:3]
	s_cbranch_vccnz .LBB0_696
	s_waitcnt lgkmcnt(0)
	v_mov_b32_e32 v1, v194
	v_writelane_b32 v234, s94, 35
	v_readfirstlane_b32 s2, v1
	s_ashr_i32 s3, s2, 6
	s_add_u32 s98, s86, 0xf000000
	s_addc_u32 s99, s87, 0
	s_add_u32 s90, s86, 0x11100000
	s_addc_u32 s91, s87, 0
	s_add_u32 s92, s86, 0x13200000
	s_addc_u32 s93, s87, 0
	s_add_u32 s4, s86, 0x8000
	v_writelane_b32 v234, s4, 36
	s_addc_u32 s4, s87, 0
	v_writelane_b32 v234, s4, 37
	s_lshl_b32 s4, s3, 5
	s_cmp_gt_u32 s2, 63
	v_writelane_b32 v234, s4, 38
	s_cselect_b64 s[4:5], -1, 0
	v_writelane_b32 v234, s4, 39
	v_and_b32_e32 v196, 63, v1
	s_lshl_b32 s2, s3, 2
	v_writelane_b32 v234, s5, 40
	v_cmp_gt_i32_e64 s[4:5], 64, v1
	s_add_i32 s2, s2, 0
	v_mov_b32_e32 v0, 0
	v_writelane_b32 v234, s4, 41
	v_and_b32_e32 v162, 48, v1
	v_mov_b32_e32 v163, v0
	v_writelane_b32 v234, s5, 42
	v_cmp_eq_u32_e64 s[4:5], 0, v196
	v_lshlrev_b32_e32 v4, 3, v1
	v_add_u32_e32 v6, 16, v1
	v_writelane_b32 v234, s4, 43
	v_ashrrev_i32_e32 v166, 4, v1
	v_lshl_add_u64 v[164:165], s[24:25], 0, v[162:163]
	v_writelane_b32 v234, s5, 44
	v_writelane_b32 v234, s2, 45
	s_add_u32 s2, s86, 0xa000
	s_addc_u32 s3, s87, 0
	v_writelane_b32 v234, s2, 46
	v_and_b32_e32 v163, 0x78, v4
	v_and_b32_e32 v33, 63, v6
	v_add_u32_e32 v6, 48, v1
	v_writelane_b32 v234, s3, 47
	v_cmp_gt_i32_e64 s[2:3], 32, v166
	v_and_b32_e32 v197, 15, v1
	v_bfe_u32 v3, v1, 4, 2
	v_cmp_eq_u32_e64 s[16:17], 0, v1
	v_lshl_add_u32 v2, v163, 1, 0
	v_and_b32_e32 v5, 3, v1
	v_and_b32_e32 v34, 63, v6
	v_bfe_u32 v6, v1, 2, 2
	v_lshlrev_b32_e32 v7, 2, v1
	v_add_u32_e32 v1, 0x200, v1
	v_writelane_b32 v234, s2, 48
	s_movk_i32 s4, 0x110
	v_ashrrev_i32_e32 v168, 4, v1
	v_writelane_b32 v234, s3, 49
	v_mad_u64_u32 v[170:171], s[2:3], v166, s4, v[2:3]
	v_cmp_gt_i32_e64 s[2:3], 32, v168
	v_and_or_b32 v1, v7, 48, v5
	v_add_u32_e32 v32, 0, v162
	v_writelane_b32 v234, s2, 50
	v_mul_u32_u24_e32 v36, 0x110, v1
	v_and_b32_e32 v201, 64, v195
	v_or_b32_e32 v6, v6, v162
	v_and_b32_e32 v4, 24, v4
	v_writelane_b32 v234, s3, 51
	v_add_u32_e32 v171, v32, v36
	v_or_b32_e32 v32, v201, v33
	v_cmp_eq_u32_e64 s[8:9], 3, v3
	v_add_u32_e32 v35, 0, v4
	v_lshlrev_b32_e32 v199, 2, v3
	v_mad_u64_u32 v[172:173], s[2:3], v168, s4, v[2:3]
	v_mul_u32_u24_e32 v37, 0x110, v6
	v_mov_b32_e32 v2, v0
	v_mov_b32_e32 v3, v0
	v_mov_b32_e32 v4, v0
	v_mov_b32_e32 v5, v0
	v_mov_b32_e32 v6, v0
	v_mov_b32_e32 v7, v0
	v_mov_b32_e32 v8, v0
	v_mov_b32_e32 v9, v0
	v_mov_b32_e32 v10, v0
	v_mov_b32_e32 v11, v0
	v_mov_b32_e32 v12, v0
	v_mov_b32_e32 v13, v0
	v_mov_b32_e32 v14, v0
	v_mov_b32_e32 v15, v0
	v_mov_b32_e32 v16, v0
	v_mov_b32_e32 v17, v0
	v_mov_b32_e32 v18, v0
	v_mov_b32_e32 v19, v0
	v_mov_b32_e32 v20, v0
	v_mov_b32_e32 v21, v0
	v_mov_b32_e32 v22, v0
	v_mov_b32_e32 v23, v0
	v_mov_b32_e32 v24, v0
	v_mov_b32_e32 v25, v0
	v_mov_b32_e32 v26, v0
	v_mov_b32_e32 v27, v0
	v_mov_b32_e32 v28, v0
	v_mov_b32_e32 v29, v0
	v_mov_b32_e32 v30, v0
	v_mov_b32_e32 v31, v0
	v_lshlrev_b32_e32 v202, 2, v32
	v_or_b32_e32 v32, v201, v34
	v_writelane_b32 v234, s96, 52
	v_mov_b32_e32 v1, v0
	v_lshlrev_b32_e32 v203, 2, v32
	v_mov_b64_e32 v[32:33], v[30:31]
	v_writelane_b32 v234, s97, 53
	s_mov_b32 s95, 0
	v_or_b32_e32 v198, 16, v197
	v_cmp_gt_u32_e64 s[10:11], 32, v196
	v_cmp_gt_u32_e64 s[12:13], 16, v196
	v_ashrrev_i32_e32 v167, 31, v166
	v_ashrrev_i32_e32 v169, 31, v168
	s_mov_b64 s[88:89], 0
	s_mov_b32 s18, -1
	v_add_u32_e32 v173, v35, v37
	v_mov_b32_e32 v200, 1
	v_mov_b64_e32 v[30:31], v[28:29]
	v_mov_b64_e32 v[28:29], v[26:27]
	v_mov_b64_e32 v[26:27], v[24:25]
	v_mov_b64_e32 v[24:25], v[22:23]
	v_mov_b64_e32 v[22:23], v[20:21]
	v_mov_b64_e32 v[20:21], v[18:19]
	v_mov_b64_e32 v[18:19], v[16:17]
	v_mov_b64_e32 v[16:17], v[14:15]
	v_mov_b64_e32 v[14:15], v[12:13]
	v_mov_b64_e32 v[12:13], v[10:11]
	v_mov_b64_e32 v[10:11], v[8:9]
	v_mov_b64_e32 v[8:9], v[6:7]
	v_mov_b64_e32 v[6:7], v[4:5]
	v_mov_b64_e32 v[4:5], v[2:3]
	v_mov_b64_e32 v[2:3], v[0:1]
	v_writelane_b32 v234, s16, 54
	s_nop 1
	v_writelane_b32 v234, s17, 55
	s_and_saveexec_b64 s[2:3], s[16:17]
	s_cbranch_execz .Ltk_init_done
	v_mov_b32_e32 v34, 1
	global_atomic_add v235, v0, v34, s[86:87] sc0
	s_waitcnt vmcnt(0)

; __device__ __forceinline__ void attn_phase(const Params& p, LAS unsigned char* lds, int cidx) {
;     ...
;     for (;;) {
;         __syncthreads();
;         if (tid == 0) misc[0] = (int)atomicAdd(ctr, 1u);
;         __syncthreads();
;         const int item = misc[0];
;         if (item >= AT_ITEMS) break;
.LBB0_603:
	s_barrier
	s_and_saveexec_b64 s[2:3], s[16:17]
	s_cbranch_execz .LBB0_607
	v_mov_b32_e32 v1, v235
	v_mov_b32_e32 v34, 1
	ds_write_b32 v0, v1 offset:34816
	s_nop 1
	global_atomic_add v235, v0, v34, s[86:87] sc0

; #define LAS __attribute__((address_space(3)))
; __device__ __forceinline__ void attn_phase(const Params& p, LAS unsigned char* lds, int cidx) {
;     ...
;             if (!wdone && kt * 64 < tpos0 + 31) {
;                 f32x4 st[2][4];
; #pragma unroll
;                 for (int mt = 0; mt < 2; ++mt)
; #pragma unroll
;                     for (int n = 0; n < 4; ++n) st[mt][n] = (f32x4){0.f, 0.f, 0.f, 0.f};
; #pragma unroll
;                 for (int kk = 0; kk < 4; ++kk)
; #pragma unroll
;                     for (int n = 0; n < 4; ++n) {
;                         const bf16x8 kf = *(const LAS bf16x8*)(Kl + (16 * (fr >> 2) + 4 * n + (fr & 3)) * AT_P + 32 * kk + 8 * fq);
;                         st[0][n] = __builtin_amdgcn_mfma_f32_16x16x32_bf16(kf, qf[0][kk], st[0][n], 0, 0, 0);
;                         st[1][n] = __builtin_amdgcn_mfma_f32_16x16x32_bf16(kf, qf[1][kk], st[1][n], 0, 0, 0);
;                     }
;                 bf16x8 pb[2][2];
;                 {
;                     const int s0 = kt * 64 + 16 * fq, tq0 = tpos0 + fr, tq1 = tpos0 + 16 + fr;
;                     f32x2 run = (f32x2){0.f, 0.f};
; #pragma unroll
;     ...
;                         const f32x2 xv = (f32x2){st[0][idx >> 2][idx & 3], st[1][idx >> 2][idx & 3]};
;                         const f32x2 ax = __builtin_elementwise_abs(xv);
;                         f32x2 e; e.x = __builtin_amdgcn_exp2f(-ax.x); e.y = __builtin_amdgcn_exp2f(-ax.y);
;                         const f32x2 e1 = e + 1.0f;
;                         f32x2 lg; lg.x = __builtin_amdgcn_logf(e1.x); lg.y = __builtin_amdgcn_logf(e1.y);
;                         const f32x2 sp = __builtin_elementwise_max(xv, (f32x2){0.f, 0.f}) + lg;
;                         const f32x2 lw = (xv - sp) + run;
;                         st[0][idx >> 2][idx & 3] = lw.x; st[1][idx >> 2][idx & 3] = lw.y;
;                         f32x2 dec; dec.x = (s0 + idx) < tq0 ? sp.x : 0.f; dec.y = (s0 + idx) < tq1 ? sp.y : 0.f;
;                         run = run - dec;
;                     }
.LBB0_674:
	s_xor_b64 s[20:21], s[20:21], -1
	s_mov_b64 s[18:19], -1
	s_waitcnt lgkmcnt(0)
	s_barrier
	s_and_saveexec_b64 s[78:79], s[20:21]
	s_cbranch_execz .LBB0_680
	s_lshl_b32 s20, s33, 6
	s_cmp_ge_i32 s20, s7
	s_mov_b64 s[18:19], 0
	s_cbranch_scc1 .LBB0_679
	ds_read_b128 v[218:221], v171
	ds_read_b128 v[222:225], v171 offset:1088
	ds_read_b128 v[226:229], v171 offset:2176
	ds_read_b128 v[230:233], v171 offset:3264
	ds_read_b128 v[236:239], v171 offset:64
	ds_read_b128 v[240:243], v171 offset:1152
	ds_read_b128 v[244:247], v171 offset:2240
	ds_read_b128 v[248:251], v171 offset:3328
	v_or_b32_e32 v1, s20, v162
	v_cmp_lt_i32_e64 s[80:81], v1, v204
	v_cmp_lt_i32_e64 s[82:83], v1, v205
	s_waitcnt lgkmcnt(7)
	v_mfma_f32_16x16x32_bf16 v[34:37], v[218:221], v[98:101], 0
	v_mfma_f32_16x16x32_bf16 v[38:41], v[218:221], v[118:121], 0
	ds_read_b128 v[218:221], v171 offset:128
	s_waitcnt lgkmcnt(7)
	v_mfma_f32_16x16x32_bf16 v[42:45], v[222:225], v[98:101], 0
	v_mfma_f32_16x16x32_bf16 v[46:49], v[222:225], v[118:121], 0
	ds_read_b128 v[222:225], v171 offset:1216
	s_waitcnt lgkmcnt(7)
	v_mfma_f32_16x16x32_bf16 v[50:53], v[226:229], v[98:101], 0
	v_mfma_f32_16x16x32_bf16 v[54:57], v[226:229], v[118:121], 0
	ds_read_b128 v[226:229], v171 offset:2304
	s_waitcnt lgkmcnt(7)
	v_mfma_f32_16x16x32_bf16 v[190:193], v[230:233], v[98:101], 0
	v_mfma_f32_16x16x32_bf16 v[206:209], v[230:233], v[118:121], 0
	ds_read_b128 v[230:233], v171 offset:3392
	s_waitcnt lgkmcnt(7)
	v_mfma_f32_16x16x32_bf16 v[34:37], v[236:239], v[102:105], v[34:37]
	v_mfma_f32_16x16x32_bf16 v[38:41], v[236:239], v[122:125], v[38:41]
	ds_read_b128 v[236:239], v171 offset:192
	s_waitcnt lgkmcnt(7)
	v_mfma_f32_16x16x32_bf16 v[42:45], v[240:243], v[102:105], v[42:45]
	v_mfma_f32_16x16x32_bf16 v[46:49], v[240:243], v[122:125], v[46:49]
	ds_read_b128 v[240:243], v171 offset:1280
	s_waitcnt lgkmcnt(7)
	v_mfma_f32_16x16x32_bf16 v[50:53], v[244:247], v[102:105], v[50:53]
	v_mfma_f32_16x16x32_bf16 v[54:57], v[244:247], v[122:125], v[54:57]
	ds_read_b128 v[244:247], v171 offset:2368
	s_waitcnt lgkmcnt(7)
	v_mfma_f32_16x16x32_bf16 v[190:193], v[248:251], v[102:105], v[190:193]
	v_mfma_f32_16x16x32_bf16 v[206:209], v[248:251], v[122:125], v[206:209]
	ds_read_b128 v[248:251], v171 offset:3456
	s_waitcnt lgkmcnt(7)
	v_mfma_f32_16x16x32_bf16 v[34:37], v[218:221], v[106:109], v[34:37]
	v_mfma_f32_16x16x32_bf16 v[38:41], v[218:221], v[126:129], v[38:41]
	s_waitcnt lgkmcnt(6)
	v_mfma_f32_16x16x32_bf16 v[42:45], v[222:225], v[106:109], v[42:45]
	v_mfma_f32_16x16x32_bf16 v[46:49], v[222:225], v[126:129], v[46:49]
	s_waitcnt lgkmcnt(5)
	v_mfma_f32_16x16x32_bf16 v[50:53], v[226:229], v[106:109], v[50:53]
	v_mfma_f32_16x16x32_bf16 v[54:57], v[226:229], v[126:129], v[54:57]
	s_waitcnt lgkmcnt(4)
	v_mfma_f32_16x16x32_bf16 v[190:193], v[230:233], v[106:109], v[190:193]
	v_mfma_f32_16x16x32_bf16 v[206:209], v[230:233], v[126:129], v[206:209]
	s_waitcnt lgkmcnt(3)
	v_mfma_f32_16x16x32_bf16 v[34:37], v[236:239], v[110:113], v[34:37]
	v_mfma_f32_16x16x32_bf16 v[38:41], v[236:239], v[130:133], v[38:41]
	s_waitcnt lgkmcnt(2)
	v_mfma_f32_16x16x32_bf16 v[42:45], v[240:243], v[110:113], v[42:45]
	v_mfma_f32_16x16x32_bf16 v[46:49], v[240:243], v[130:133], v[46:49]
	s_waitcnt lgkmcnt(1)
	v_mfma_f32_16x16x32_bf16 v[50:53], v[244:247], v[110:113], v[50:53]
	v_mfma_f32_16x16x32_bf16 v[54:57], v[244:247], v[130:133], v[54:57]
	s_waitcnt lgkmcnt(0)
	v_mfma_f32_16x16x32_bf16 v[190:193], v[248:251], v[110:113], v[190:193]
	v_mfma_f32_16x16x32_bf16 v[206:209], v[248:251], v[130:133], v[206:209]
	s_nop 6
	v_exp_f32_e64 v62, -|v193|
	v_mov_b32_e32 v60, v193
	v_exp_f32_e64 v63, -|v209|
	v_max_f32_e32 v64, v209, v209
	v_max_f32_e32 v65, 0, v64
	v_max_f32_e32 v64, v193, v193
	v_pk_add_f32 v[62:63], v[62:63], 1.0 op_sel_hi:[1,0]
	v_max_f32_e32 v64, 0, v64
	v_log_f32_e32 v62, v62
	v_log_f32_e32 v63, v63
	v_mov_b32_e32 v61, v209
	v_mov_b32_e32 v193, v208
	v_pk_add_f32 v[62:63], v[64:65], v[62:63]
	v_or_b32_e32 v64, 15, v1
	v_cmp_lt_i32_e64 s[18:19], v64, v204
	v_cmp_lt_i32_e32 vcc, v64, v205
	v_pk_add_f32 v[60:61], v[60:61], v[62:63] neg_lo:[0,1] neg_hi:[0,1]
	v_cndmask_b32_e64 v62, 0, v62, s[18:19]
	v_cndmask_b32_e32 v63, 0, v63, vcc
	v_pk_add_f32 v[64:65], v[62:63], 0 op_sel_hi:[1,0] neg_lo:[1,0] neg_hi:[1,0]
	v_exp_f32_e64 v62, -|v192|
	v_exp_f32_e64 v63, -|v208|
	v_max_f32_e32 v208, v208, v208
	v_max_f32_e32 v209, 0, v208
	v_max_f32_e32 v208, v192, v192
	v_pk_add_f32 v[62:63], v[62:63], 1.0 op_sel_hi:[1,0]
	v_max_f32_e32 v208, 0, v208
	v_log_f32_e32 v62, v62
	v_log_f32_e32 v63, v63
	v_pk_add_f32 v[60:61], v[60:61], 0 op_sel_hi:[1,0]
	v_pk_add_f32 v[208:209], v[208:209], v[62:63]
	s_nop 0
	v_pk_add_f32 v[62:63], v[192:193], v[208:209] neg_lo:[0,1] neg_hi:[0,1]
	v_or_b32_e32 v193, 14, v1
	v_cmp_lt_i32_e64 s[22:23], v193, v204
	v_cmp_lt_i32_e64 s[20:21], v193, v205
	v_pk_add_f32 v[62:63], v[62:63], v[64:65]
	v_cndmask_b32_e64 v192, 0, v208, s[22:23]
	v_cndmask_b32_e64 v193, 0, v209, s[20:21]
	v_exp_f32_e64 v208, -|v191|
	v_exp_f32_e64 v209, -|v207|
	v_pk_add_f32 v[192:193], v[64:65], v[192:193] neg_lo:[0,1] neg_hi:[0,1]
	v_mov_b32_e32 v64, v191
	v_mov_b32_e32 v65, v207
	v_pk_add_f32 v[208:209], v[208:209], 1.0 op_sel_hi:[1,0]
	v_max_f32_e32 v207, v207, v207
	v_log_f32_e32 v208, v208
	v_log_f32_e32 v209, v209
	v_max_f32_e32 v191, v191, v191
	v_max_f32_e32 v211, 0, v207
	v_max_f32_e32 v210, 0, v191
	v_or_b32_e32 v191, 13, v1
	v_pk_add_f32 v[208:209], v[210:211], v[208:209]
	v_cmp_lt_i32_e64 s[26:27], v191, v204
	v_cmp_lt_i32_e64 s[24:25], v191, v205
	v_pk_add_f32 v[64:65], v[64:65], v[208:209] neg_lo:[0,1] neg_hi:[0,1]
; __device__ __forceinline__ void attn_phase(const Params& p, LAS unsigned char* lds, int cidx) {
;     ...
; #pragma unroll
;     ...
;                         const f32x2 xv = (f32x2){st[0][idx >> 2][idx & 3], st[1][idx >> 2][idx & 3]};
;                         const f32x2 ax = __builtin_elementwise_abs(xv);
;                         f32x2 e; e.x = __builtin_amdgcn_exp2f(-ax.x); e.y = __builtin_amdgcn_exp2f(-ax.y);
;                         const f32x2 e1 = e + 1.0f;
;                         f32x2 lg; lg.x = __builtin_amdgcn_logf(e1.x); lg.y = __builtin_amdgcn_logf(e1.y);
;                         const f32x2 sp = __builtin_elementwise_max(xv, (f32x2){0.f, 0.f}) + lg;
;                         const f32x2 lw = (xv - sp) + run;
;                         st[0][idx >> 2][idx & 3] = lw.x; st[1][idx >> 2][idx & 3] = lw.y;
;                         f32x2 dec; dec.x = (s0 + idx) < tq0 ? sp.x : 0.f; dec.y = (s0 + idx) < tq1 ? sp.y : 0.f;
;                         run = run - dec;
;                     }
	v_cndmask_b32_e64 v208, 0, v208, s[26:27]
	v_cndmask_b32_e64 v209, 0, v209, s[24:25]
	v_pk_add_f32 v[64:65], v[64:65], v[192:193]
	v_pk_add_f32 v[192:193], v[192:193], v[208:209] neg_lo:[0,1] neg_hi:[0,1]
	v_exp_f32_e64 v208, -|v190|
	v_exp_f32_e64 v209, -|v206|
	v_mov_b32_e32 v191, v206
	v_max_f32_e32 v206, v206, v206
	v_max_f32_e32 v207, 0, v206
	v_pk_add_f32 v[208:209], v[208:209], 1.0 op_sel_hi:[1,0]
	v_max_f32_e32 v206, v190, v190
	v_log_f32_e32 v208, v208
	v_log_f32_e32 v209, v209
	v_max_f32_e32 v206, 0, v206
	v_pk_add_f32 v[206:207], v[206:207], v[208:209]
	v_or_b32_e32 v208, 12, v1
	v_cmp_lt_i32_e64 s[28:29], v208, v204
	v_cmp_lt_i32_e64 s[30:31], v208, v205
	v_exp_f32_e64 v208, -|v53|
	v_exp_f32_e64 v209, -|v57|
	v_pk_add_f32 v[190:191], v[190:191], v[206:207] neg_lo:[0,1] neg_hi:[0,1]
	v_cndmask_b32_e64 v206, 0, v206, s[28:29]
	v_cndmask_b32_e64 v207, 0, v207, s[30:31]
	v_pk_add_f32 v[208:209], v[208:209], 1.0 op_sel_hi:[1,0]
	v_pk_add_f32 v[190:191], v[190:191], v[192:193]
	v_log_f32_e32 v208, v208
	v_log_f32_e32 v209, v209
	v_pk_add_f32 v[206:207], v[192:193], v[206:207] neg_lo:[0,1] neg_hi:[0,1]
	v_mov_b32_e32 v192, v53
	v_mov_b32_e32 v193, v57
	v_max_f32_e32 v57, v57, v57
	v_max_f32_e32 v53, v53, v53
	v_max_f32_e32 v211, 0, v57
	v_max_f32_e32 v210, 0, v53
	v_or_b32_e32 v53, 11, v1
	v_pk_add_f32 v[208:209], v[210:211], v[208:209]
	v_cmp_lt_i32_e64 s[36:37], v53, v204
	v_cmp_lt_i32_e64 s[34:35], v53, v205
	v_pk_add_f32 v[192:193], v[192:193], v[208:209] neg_lo:[0,1] neg_hi:[0,1]
	v_cndmask_b32_e64 v208, 0, v208, s[36:37]
	v_cndmask_b32_e64 v209, 0, v209, s[34:35]
	v_pk_add_f32 v[192:193], v[192:193], v[206:207]
	v_pk_add_f32 v[206:207], v[206:207], v[208:209] neg_lo:[0,1] neg_hi:[0,1]
	v_exp_f32_e64 v208, -|v52|
	v_exp_f32_e64 v209, -|v56|
	v_mov_b32_e32 v53, v56
	v_max_f32_e32 v56, v56, v56
	v_max_f32_e32 v57, 0, v56
	v_pk_add_f32 v[208:209], v[208:209], 1.0 op_sel_hi:[1,0]
	v_max_f32_e32 v56, v52, v52
	v_log_f32_e32 v208, v208
	v_log_f32_e32 v209, v209
	v_max_f32_e32 v56, 0, v56
	v_pk_add_f32 v[56:57], v[56:57], v[208:209]
	v_or_b32_e32 v208, 10, v1
	v_cmp_lt_i32_e64 s[40:41], v208, v204
	v_cmp_lt_i32_e64 s[38:39], v208, v205
	v_exp_f32_e64 v208, -|v51|
	v_exp_f32_e64 v209, -|v55|
	v_pk_add_f32 v[52:53], v[52:53], v[56:57] neg_lo:[0,1] neg_hi:[0,1]
	v_cndmask_b32_e64 v56, 0, v56, s[40:41]
	v_cndmask_b32_e64 v57, 0, v57, s[38:39]
	v_pk_add_f32 v[208:209], v[208:209], 1.0 op_sel_hi:[1,0]
	v_pk_add_f32 v[52:53], v[52:53], v[206:207]
	v_log_f32_e32 v208, v208
	v_log_f32_e32 v209, v209
	v_pk_add_f32 v[206:207], v[206:207], v[56:57] neg_lo:[0,1] neg_hi:[0,1]
	v_mov_b32_e32 v56, v51
	v_mov_b32_e32 v57, v55
	v_max_f32_e32 v55, v55, v55
	v_max_f32_e32 v51, v51, v51
	v_max_f32_e32 v211, 0, v55
	v_max_f32_e32 v210, 0, v51
	v_or_b32_e32 v51, 9, v1
	v_pk_add_f32 v[208:209], v[210:211], v[208:209]
	v_cmp_lt_i32_e64 s[44:45], v51, v204
	v_cmp_lt_i32_e64 s[42:43], v51, v205
	v_pk_add_f32 v[56:57], v[56:57], v[208:209] neg_lo:[0,1] neg_hi:[0,1]
	v_cndmask_b32_e64 v208, 0, v208, s[44:45]
	v_cndmask_b32_e64 v209, 0, v209, s[42:43]
	v_pk_add_f32 v[56:57], v[56:57], v[206:207]
	v_pk_add_f32 v[206:207], v[206:207], v[208:209] neg_lo:[0,1] neg_hi:[0,1]
	v_exp_f32_e64 v208, -|v50|
	v_exp_f32_e64 v209, -|v54|
	v_mov_b32_e32 v51, v54
	v_max_f32_e32 v54, v54, v54
	v_max_f32_e32 v55, 0, v54
	v_pk_add_f32 v[208:209], v[208:209], 1.0 op_sel_hi:[1,0]
	v_max_f32_e32 v54, v50, v50
	v_log_f32_e32 v208, v208
	v_log_f32_e32 v209, v209
	v_max_f32_e32 v54, 0, v54
	v_pk_add_f32 v[54:55], v[54:55], v[208:209]
	v_or_b32_e32 v208, 8, v1
	v_cmp_lt_i32_e64 s[48:49], v208, v204
	v_cmp_lt_i32_e64 s[46:47], v208, v205
	v_exp_f32_e64 v208, -|v45|
	v_exp_f32_e64 v209, -|v49|
	v_pk_add_f32 v[50:51], v[50:51], v[54:55] neg_lo:[0,1] neg_hi:[0,1]
	v_cndmask_b32_e64 v54, 0, v54, s[48:49]
	v_cndmask_b32_e64 v55, 0, v55, s[46:47]
	v_pk_add_f32 v[208:209], v[208:209], 1.0 op_sel_hi:[1,0]
	v_pk_add_f32 v[50:51], v[50:51], v[206:207]
	v_log_f32_e32 v208, v208
	v_log_f32_e32 v209, v209
	v_pk_add_f32 v[206:207], v[206:207], v[54:55] neg_lo:[0,1] neg_hi:[0,1]
	v_mov_b32_e32 v54, v45
	v_mov_b32_e32 v55, v49
	v_max_f32_e32 v49, v49, v49
	v_max_f32_e32 v45, v45, v45
	v_max_f32_e32 v211, 0, v49
	v_max_f32_e32 v210, 0, v45
	v_or_b32_e32 v45, 7, v1
	v_pk_add_f32 v[208:209], v[210:211], v[208:209]
	v_cmp_lt_i32_e64 s[52:53], v45, v204
	v_cmp_lt_i32_e64 s[50:51], v45, v205
	v_pk_add_f32 v[54:55], v[54:55], v[208:209] neg_lo:[0,1] neg_hi:[0,1]
	v_cndmask_b32_e64 v208, 0, v208, s[52:53]
	v_cndmask_b32_e64 v209, 0, v209, s[50:51]
	v_pk_add_f32 v[54:55], v[54:55], v[206:207]
	v_pk_add_f32 v[206:207], v[206:207], v[208:209] neg_lo:[0,1] neg_hi:[0,1]
	v_exp_f32_e64 v208, -|v44|
	v_exp_f32_e64 v209, -|v48|
	v_mov_b32_e32 v45, v48
	v_max_f32_e32 v48, v48, v48
	v_max_f32_e32 v49, 0, v48
	v_pk_add_f32 v[208:209], v[208:209], 1.0 op_sel_hi:[1,0]
	v_max_f32_e32 v48, v44, v44
	v_log_f32_e32 v208, v208
	v_log_f32_e32 v209, v209
	v_max_f32_e32 v48, 0, v48
	v_pk_add_f32 v[48:49], v[48:49], v[208:209]
	v_or_b32_e32 v208, 6, v1
	v_cmp_lt_i32_e64 s[56:57], v208, v204
	v_cmp_lt_i32_e64 s[54:55], v208, v205
	v_exp_f32_e64 v208, -|v43|
	v_exp_f32_e64 v209, -|v47|
	v_pk_add_f32 v[44:45], v[44:45], v[48:49] neg_lo:[0,1] neg_hi:[0,1]
	v_cndmask_b32_e64 v48, 0, v48, s[56:57]
	v_cndmask_b32_e64 v49, 0, v49, s[54:55]
	v_pk_add_f32 v[208:209], v[208:209], 1.0 op_sel_hi:[1,0]
	v_pk_add_f32 v[44:45], v[44:45], v[206:207]
	v_log_f32_e32 v208, v208
	v_log_f32_e32 v209, v209
	v_pk_add_f32 v[206:207], v[206:207], v[48:49] neg_lo:[0,1] neg_hi:[0,1]
	v_mov_b32_e32 v48, v43
	v_mov_b32_e32 v49, v47
	v_max_f32_e32 v47, v47, v47
; __device__ __forceinline__ void attn_phase(const Params& p, LAS unsigned char* lds, int cidx) {
;     ...
; #pragma unroll
;     ...
;                         const f32x2 xv = (f32x2){st[0][idx >> 2][idx & 3], st[1][idx >> 2][idx & 3]};
;                         const f32x2 ax = __builtin_elementwise_abs(xv);
;                         f32x2 e; e.x = __builtin_amdgcn_exp2f(-ax.x); e.y = __builtin_amdgcn_exp2f(-ax.y);
;                         const f32x2 e1 = e + 1.0f;
;                         f32x2 lg; lg.x = __builtin_amdgcn_logf(e1.x); lg.y = __builtin_amdgcn_logf(e1.y);
;                         const f32x2 sp = __builtin_elementwise_max(xv, (f32x2){0.f, 0.f}) + lg;
;                         const f32x2 lw = (xv - sp) + run;
;                         st[0][idx >> 2][idx & 3] = lw.x; st[1][idx >> 2][idx & 3] = lw.y;
;                         f32x2 dec; dec.x = (s0 + idx) < tq0 ? sp.x : 0.f; dec.y = (s0 + idx) < tq1 ? sp.y : 0.f;
;                         run = run - dec;
;                     }
;                     f32x2 t16, t32, t48;
;                     t16.x = __shfl(run.x, (lane + 16) & 63); t16.y = __shfl(run.y, (lane + 16) & 63);
;                     t32.x = __shfl(run.x, (lane + 32) & 63); t32.y = __shfl(run.y, (lane + 32) & 63);
;                     t48.x = __shfl(run.x, (lane + 48) & 63); t48.y = __shfl(run.y, (lane + 48) & 63);
;                     const f32x2 z2 = (f32x2){0.f, 0.f};
;                     const f32x2 higher = (fq < 3 ? t16 : z2) + (fq < 2 ? t32 : z2) + (fq < 1 ? t48 : z2);
;                     const f32x2 base = (f32x2){C[0], C[1]} + higher;
;                     const f32x2 tot = (run + t16) + (t32 + t48);
;                     C[0] += tot.x; C[1] += tot.y;
	v_max_f32_e32 v43, v43, v43
	v_max_f32_e32 v211, 0, v47
	v_max_f32_e32 v210, 0, v43
	v_or_b32_e32 v43, 5, v1
	v_pk_add_f32 v[208:209], v[210:211], v[208:209]
	v_cmp_lt_i32_e64 s[60:61], v43, v204
	v_cmp_lt_i32_e64 s[58:59], v43, v205
	v_pk_add_f32 v[48:49], v[48:49], v[208:209] neg_lo:[0,1] neg_hi:[0,1]
	v_cndmask_b32_e64 v208, 0, v208, s[60:61]
	v_cndmask_b32_e64 v209, 0, v209, s[58:59]
	v_pk_add_f32 v[48:49], v[48:49], v[206:207]
	v_pk_add_f32 v[206:207], v[206:207], v[208:209] neg_lo:[0,1] neg_hi:[0,1]
	v_exp_f32_e64 v208, -|v42|
	v_exp_f32_e64 v209, -|v46|
	v_mov_b32_e32 v43, v46
	v_max_f32_e32 v46, v46, v46
	v_max_f32_e32 v47, 0, v46
	v_pk_add_f32 v[208:209], v[208:209], 1.0 op_sel_hi:[1,0]
	v_max_f32_e32 v46, v42, v42
	v_log_f32_e32 v208, v208
	v_log_f32_e32 v209, v209
	v_max_f32_e32 v46, 0, v46
	v_pk_add_f32 v[208:209], v[46:47], v[208:209]
	s_nop 0
	v_pk_add_f32 v[42:43], v[42:43], v[208:209] neg_lo:[0,1] neg_hi:[0,1]
	s_nop 0
	v_pk_add_f32 v[46:47], v[42:43], v[206:207]
	v_or_b32_e32 v43, 4, v1
	v_cmp_lt_i32_e64 s[64:65], v43, v204
	v_cmp_lt_i32_e64 s[62:63], v43, v205
	s_nop 0
	v_cndmask_b32_e64 v42, 0, v208, s[64:65]
	v_cndmask_b32_e64 v43, 0, v209, s[62:63]
	v_exp_f32_e64 v208, -|v37|
	v_exp_f32_e64 v209, -|v41|
	v_pk_add_f32 v[42:43], v[206:207], v[42:43] neg_lo:[0,1] neg_hi:[0,1]
	v_mov_b32_e32 v206, v37
	v_mov_b32_e32 v207, v41
	v_pk_add_f32 v[208:209], v[208:209], 1.0 op_sel_hi:[1,0]
	v_max_f32_e32 v41, v41, v41
	v_log_f32_e32 v208, v208
	v_log_f32_e32 v209, v209
	v_max_f32_e32 v37, v37, v37
	v_max_f32_e32 v211, 0, v41
	v_max_f32_e32 v210, 0, v37
	v_or_b32_e32 v37, 3, v1
	v_pk_add_f32 v[208:209], v[210:211], v[208:209]
	v_cmp_lt_i32_e64 s[68:69], v37, v204
	v_cmp_lt_i32_e64 s[66:67], v37, v205
	v_pk_add_f32 v[206:207], v[206:207], v[208:209] neg_lo:[0,1] neg_hi:[0,1]
	v_cndmask_b32_e64 v208, 0, v208, s[68:69]
	v_cndmask_b32_e64 v209, 0, v209, s[66:67]
	v_pk_add_f32 v[206:207], v[206:207], v[42:43]
	v_pk_add_f32 v[42:43], v[42:43], v[208:209] neg_lo:[0,1] neg_hi:[0,1]
	v_exp_f32_e64 v208, -|v36|
	v_exp_f32_e64 v209, -|v40|
	v_mov_b32_e32 v37, v40
	v_max_f32_e32 v40, v40, v40
	v_max_f32_e32 v41, 0, v40
	v_pk_add_f32 v[208:209], v[208:209], 1.0 op_sel_hi:[1,0]
	v_max_f32_e32 v40, v36, v36
	v_log_f32_e32 v208, v208
	v_log_f32_e32 v209, v209
	v_max_f32_e32 v40, 0, v40
	v_pk_add_f32 v[40:41], v[40:41], v[208:209]
	v_or_b32_e32 v208, 2, v1
	v_cmp_lt_i32_e64 s[72:73], v208, v204
	v_cmp_lt_i32_e64 s[70:71], v208, v205
	v_exp_f32_e64 v208, -|v35|
	v_exp_f32_e64 v209, -|v39|
	v_pk_add_f32 v[36:37], v[36:37], v[40:41] neg_lo:[0,1] neg_hi:[0,1]
	v_cndmask_b32_e64 v40, 0, v40, s[72:73]
	v_cndmask_b32_e64 v41, 0, v41, s[70:71]
	v_pk_add_f32 v[208:209], v[208:209], 1.0 op_sel_hi:[1,0]
	v_pk_add_f32 v[36:37], v[36:37], v[42:43]
	v_log_f32_e32 v208, v208
	v_log_f32_e32 v209, v209
	v_pk_add_f32 v[40:41], v[42:43], v[40:41] neg_lo:[0,1] neg_hi:[0,1]
	v_mov_b32_e32 v42, v35
	v_mov_b32_e32 v43, v39
	v_max_f32_e32 v39, v39, v39
	v_max_f32_e32 v35, v35, v35
	v_max_f32_e32 v211, 0, v39
	v_max_f32_e32 v210, 0, v35
	v_pk_add_f32 v[208:209], v[210:211], v[208:209]
	v_or_b32_e32 v35, 1, v1
	v_pk_add_f32 v[42:43], v[42:43], v[208:209] neg_lo:[0,1] neg_hi:[0,1]
	v_cmp_lt_i32_e64 s[76:77], v35, v204
	v_cmp_lt_i32_e64 s[74:75], v35, v205
	v_pk_add_f32 v[210:211], v[42:43], v[40:41]
	v_cndmask_b32_e64 v42, 0, v208, s[76:77]
	v_cndmask_b32_e64 v43, 0, v209, s[74:75]
	v_pk_add_f32 v[40:41], v[40:41], v[42:43] neg_lo:[0,1] neg_hi:[0,1]
	v_exp_f32_e64 v42, -|v34|
	v_exp_f32_e64 v43, -|v38|
	v_mov_b32_e32 v35, v38
	v_max_f32_e32 v38, v38, v38
	v_max_f32_e32 v39, 0, v38
	v_pk_add_f32 v[42:43], v[42:43], 1.0 op_sel_hi:[1,0]
	v_max_f32_e32 v38, v34, v34
	v_log_f32_e32 v42, v42
	v_log_f32_e32 v43, v43
	v_max_f32_e32 v38, 0, v38
	v_or_b32_e32 v1, v201, v196
	v_lshlrev_b32_e32 v1, 2, v1
	v_pk_add_f32 v[38:39], v[38:39], v[42:43]
	v_xor_b32_e32 v1, 0x80, v1
	v_pk_add_f32 v[34:35], v[34:35], v[38:39] neg_lo:[0,1] neg_hi:[0,1]
	v_cndmask_b32_e64 v38, 0, v38, s[80:81]
	v_cndmask_b32_e64 v39, 0, v39, s[82:83]
	v_pk_add_f32 v[38:39], v[40:41], v[38:39] neg_lo:[0,1] neg_hi:[0,1]
	v_pk_add_f32 v[34:35], v[34:35], v[40:41]
	ds_bpermute_b32 v40, v202, v38
	ds_bpermute_b32 v41, v202, v39
	ds_bpermute_b32 v42, v1, v38
	ds_bpermute_b32 v43, v1, v39
	ds_bpermute_b32 v208, v203, v38
	ds_bpermute_b32 v209, v203, v39
	s_waitcnt lgkmcnt(4)
	v_cndmask_b32_e64 v213, v41, 0, s[8:9]
	v_cndmask_b32_e64 v212, v40, 0, s[8:9]
	s_waitcnt lgkmcnt(2)
	v_cndmask_b32_e64 v215, 0, v43, s[10:11]
	v_cndmask_b32_e64 v214, 0, v42, s[10:11]
	v_pk_add_f32 v[212:213], v[212:213], v[214:215]
	s_waitcnt lgkmcnt(0)
; #define LAS __attribute__((address_space(3)))
; __device__ __forceinline__ void attn_phase(const Params& p, LAS unsigned char* lds, int cidx) {
;     ...
;                     f32x2 t16, t32, t48;
;                     t16.x = __shfl(run.x, (lane + 16) & 63); t16.y = __shfl(run.y, (lane + 16) & 63);
;                     t32.x = __shfl(run.x, (lane + 32) & 63); t32.y = __shfl(run.y, (lane + 32) & 63);
;                     t48.x = __shfl(run.x, (lane + 48) & 63); t48.y = __shfl(run.y, (lane + 48) & 63);
;                     const f32x2 z2 = (f32x2){0.f, 0.f};
;                     const f32x2 higher = (fq < 3 ? t16 : z2) + (fq < 2 ? t32 : z2) + (fq < 1 ? t48 : z2);
;                     const f32x2 base = (f32x2){C[0], C[1]} + higher;
;                     const f32x2 tot = (run + t16) + (t32 + t48);
;                     C[0] += tot.x; C[1] += tot.y;
;                     float w0[16], w1[16];
; #pragma unroll
;                     for (int idx = 0; idx < 16; ++idx) {
;                         const f32x2 a2 = (f32x2){st[0][idx >> 2][idx & 3], st[1][idx >> 2][idx & 3]} + base;
;                         w0[idx] = (s0 + idx) < tq0 ? __builtin_amdgcn_exp2f(a2.x) : 0.f;
;                         w1[idx] = (s0 + idx) < tq1 ? __builtin_amdgcn_exp2f(a2.y) : 0.f;
;                     }
; #pragma unroll
;                     for (int k2 = 0; k2 < 2; ++k2) {
;                         u32x4 pw; pw.x = cvt_pk_bf16(w0[8 * k2 + 0], w0[8 * k2 + 1]); pw.y = cvt_pk_bf16(w0[8 * k2 + 2], w0[8 * k2 + 3]); pw.z = cvt_pk_bf16(w0[8 * k2 + 4], w0[8 * k2 + 5]); pw.w = cvt_pk_bf16(w0[8 * k2 + 6], w0[8 * k2 + 7]);
;                         pb[0][k2] = __builtin_bit_cast(bf16x8, pw);
;                         u32x4 pv; pv.x = cvt_pk_bf16(w1[8 * k2 + 0], w1[8 * k2 + 1]); pv.y = cvt_pk_bf16(w1[8 * k2 + 2], w1[8 * k2 + 3]); pv.z = cvt_pk_bf16(w1[8 * k2 + 4], w1[8 * k2 + 5]); pv.w = cvt_pk_bf16(w1[8 * k2 + 6], w1[8 * k2 + 7]);
;                         pb[1][k2] = __builtin_bit_cast(bf16x8, pv);
;                     }
;                 }
; #pragma unroll
;                 for (int k2 = 0; k2 < 2; ++k2)
; #pragma unroll
;                     for (int dt = 0; dt < 8; ++dt) {
;                         const LAS bf16_t* a0 = Vl + (16 * fq + 8 * k2 + (fr >> 2)) * AT_P + 16 * dt + 4 * (fr & 3);
	v_cndmask_b32_e64 v215, 0, v209, s[12:13]
	v_cndmask_b32_e64 v214, 0, v208, s[12:13]
	v_pk_add_f32 v[212:213], v[212:213], v[214:215]
	v_pk_add_f32 v[38:39], v[38:39], v[40:41]
	v_pk_add_f32 v[212:213], v[58:59], v[212:213]
	v_pk_add_f32 v[40:41], v[42:43], v[208:209]
	v_pk_add_f32 v[34:35], v[212:213], v[34:35]
	v_pk_add_f32 v[42:43], v[40:41], v[38:39]
	v_exp_f32_e32 v1, v34
	v_exp_f32_e32 v34, v35
	v_pk_add_f32 v[58:59], v[58:59], v[42:43]
	v_cndmask_b32_e64 v1, 0, v1, s[80:81]
	v_cndmask_b32_e64 v38, 0, v34, s[82:83]
	v_pk_add_f32 v[34:35], v[212:213], v[210:211]
	s_nop 0
	v_exp_f32_e32 v34, v34
	s_nop 0
	v_cndmask_b32_e64 v39, 0, v34, s[76:77]
	v_exp_f32_e32 v34, v35
	s_nop 0
	v_cndmask_b32_e64 v40, 0, v34, s[74:75]
	v_pk_add_f32 v[34:35], v[212:213], v[36:37]
	s_nop 0
	v_exp_f32_e32 v34, v34
	s_nop 0
	v_cndmask_b32_e64 v36, 0, v34, s[72:73]
	v_exp_f32_e32 v34, v35
	s_nop 0
	v_cndmask_b32_e64 v37, 0, v34, s[70:71]
	v_pk_add_f32 v[34:35], v[212:213], v[206:207]
	s_nop 0
	v_exp_f32_e32 v34, v34
	s_nop 0
	v_cndmask_b32_e64 v41, 0, v34, s[68:69]
	v_exp_f32_e32 v34, v35
	s_nop 0
	v_cndmask_b32_e64 v206, 0, v34, s[66:67]
	v_pk_add_f32 v[34:35], v[212:213], v[46:47]
	s_nop 0
	v_exp_f32_e32 v34, v34
	s_nop 0
	v_cndmask_b32_e64 v46, 0, v34, s[64:65]
	v_exp_f32_e32 v34, v35
	s_nop 0
	v_cndmask_b32_e64 v207, 0, v34, s[62:63]
	v_pk_add_f32 v[34:35], v[212:213], v[48:49]
	s_nop 0
	v_exp_f32_e32 v34, v34
	s_nop 0
	v_cndmask_b32_e64 v47, 0, v34, s[60:61]
	v_exp_f32_e32 v34, v35
	s_nop 0
	v_cndmask_b32_e64 v208, 0, v34, s[58:59]
	v_pk_add_f32 v[34:35], v[212:213], v[44:45]
	v_cvt_pk_bf16_f32 v44, v1, v39
	v_cvt_pk_bf16_f32 v45, v36, v41
	v_cvt_pk_bf16_f32 v46, v46, v47
	s_nop 0
	v_exp_f32_e32 v34, v34
	s_nop 0
	v_cndmask_b32_e64 v48, 0, v34, s[56:57]
	v_exp_f32_e32 v34, v35
	s_nop 0
	v_cndmask_b32_e64 v209, 0, v34, s[54:55]
	v_pk_add_f32 v[34:35], v[212:213], v[54:55]
	s_nop 0
	v_exp_f32_e32 v34, v34
	s_nop 0
	v_cndmask_b32_e64 v49, 0, v34, s[52:53]
	v_exp_f32_e32 v34, v35
	v_cvt_pk_bf16_f32 v47, v48, v49
	v_cvt_pk_bf16_f32 v48, v38, v40
	v_cvt_pk_bf16_f32 v49, v37, v206
	s_nop 0
	v_cndmask_b32_e64 v54, 0, v34, s[50:51]
	v_pk_add_f32 v[34:35], v[212:213], v[50:51]
	v_cvt_pk_bf16_f32 v50, v207, v208
	v_cvt_pk_bf16_f32 v51, v209, v54
	s_nop 0
	v_exp_f32_e32 v34, v34
	s_nop 0
	v_cndmask_b32_e64 v55, 0, v34, s[48:49]
	v_exp_f32_e32 v34, v35
	s_nop 0
	v_cndmask_b32_e64 v210, 0, v34, s[46:47]
	v_pk_add_f32 v[34:35], v[212:213], v[56:57]
	s_nop 0
	v_exp_f32_e32 v34, v34
	s_nop 0
	v_cndmask_b32_e64 v56, 0, v34, s[44:45]
	v_exp_f32_e32 v34, v35
	v_cvt_pk_bf16_f32 v38, v55, v56
	s_nop 0
	v_cndmask_b32_e64 v57, 0, v34, s[42:43]
	v_pk_add_f32 v[34:35], v[212:213], v[52:53]
	s_nop 0
	v_exp_f32_e32 v34, v34
	s_nop 0
	v_cndmask_b32_e64 v52, 0, v34, s[40:41]
	v_exp_f32_e32 v34, v35
	s_nop 0
	v_cndmask_b32_e64 v53, 0, v34, s[38:39]
	v_pk_add_f32 v[34:35], v[212:213], v[192:193]
	s_nop 0
	v_exp_f32_e32 v34, v34
	s_nop 0
	v_cndmask_b32_e64 v192, 0, v34, s[36:37]
	v_exp_f32_e32 v34, v35
	v_cvt_pk_bf16_f32 v39, v52, v192
	s_nop 0
	v_cndmask_b32_e64 v193, 0, v34, s[34:35]
	v_pk_add_f32 v[34:35], v[212:213], v[190:191]
	s_nop 0
	v_exp_f32_e32 v34, v34
	s_nop 0
	v_cndmask_b32_e64 v190, 0, v34, s[28:29]
	v_exp_f32_e32 v34, v35
	s_nop 0
	v_cndmask_b32_e64 v191, 0, v34, s[30:31]
	v_pk_add_f32 v[34:35], v[212:213], v[64:65]
	s_nop 0
	v_exp_f32_e32 v34, v34
	s_nop 0
	v_cndmask_b32_e64 v64, 0, v34, s[26:27]
	v_exp_f32_e32 v34, v35
	v_cvt_pk_bf16_f32 v40, v190, v64
	s_nop 0
	v_cndmask_b32_e64 v65, 0, v34, s[24:25]
	v_pk_add_f32 v[34:35], v[212:213], v[62:63]
	s_nop 0
	v_exp_f32_e32 v34, v34
	s_nop 0
	v_cndmask_b32_e64 v62, 0, v34, s[22:23]
	v_exp_f32_e32 v34, v35
	s_nop 0
	v_cndmask_b32_e64 v63, 0, v34, s[20:21]
	v_pk_add_f32 v[34:35], v[212:213], v[60:61]
	v_readlane_b32 s20, v234, 43
	v_exp_f32_e32 v34, v34
	v_exp_f32_e32 v35, v35
	v_readlane_b32 s21, v234, 44
	v_cndmask_b32_e64 v34, 0, v34, s[18:19]
	v_cndmask_b32_e32 v60, 0, v35, vcc
	v_cvt_pk_bf16_f32 v41, v62, v34
	v_cvt_pk_bf16_f32 v34, v210, v57
	v_cvt_pk_bf16_f32 v35, v53, v193
	v_cvt_pk_bf16_f32 v36, v191, v65
	v_cvt_pk_bf16_f32 v37, v63, v60
	ds_read_b64_tr_b16 v[218:219], v173 offset:17408
	ds_read_b64_tr_b16 v[220:221], v173 offset:18496
	ds_read_b64_tr_b16 v[222:223], v173 offset:17440
	ds_read_b64_tr_b16 v[224:225], v173 offset:18528
	ds_read_b64_tr_b16 v[226:227], v173 offset:17472
	ds_read_b64_tr_b16 v[228:229], v173 offset:18560
	ds_read_b64_tr_b16 v[230:231], v173 offset:17504
	ds_read_b64_tr_b16 v[232:233], v173 offset:18592
	ds_read_b64_tr_b16 v[236:237], v173 offset:17536
	ds_read_b64_tr_b16 v[238:239], v173 offset:18624
	ds_read_b64_tr_b16 v[240:241], v173 offset:17568
	ds_read_b64_tr_b16 v[242:243], v173 offset:18656
	s_mov_b32 s18, 0xc3200000
	v_cmp_gt_f32_e32 vcc, s18, v58
	v_cmp_gt_f32_e64 s[18:19], s18, v59
	s_waitcnt lgkmcnt(10)
; #define LAS __attribute__((address_space(3)))
; __device__ __forceinline__ void attn_phase(const Params& p, LAS unsigned char* lds, int cidx) {
;     ...
; #pragma unroll
;                 for (int k2 = 0; k2 < 2; ++k2)
; #pragma unroll
;                     for (int dt = 0; dt < 8; ++dt) {
;                         const LAS bf16_t* a0 = Vl + (16 * fq + 8 * k2 + (fr >> 2)) * AT_P + 16 * dt + 4 * (fr & 3);
;                         const s16x4 lo = __builtin_amdgcn_ds_read_tr16_b64_v4i16((LAS s16x4*)a0), hi = __builtin_amdgcn_ds_read_tr16_b64_v4i16((LAS s16x4*)(a0 + 4 * AT_P));
;                         const bf16x8 vf = (bf16x8){lo[0], lo[1], lo[2], lo[3], hi[0], hi[1], hi[2], hi[3]};
;                         o[0][dt] = __builtin_amdgcn_mfma_f32_16x16x32_bf16(vf, pb[0][k2], o[0][dt], 0, 0, 0);
;                         o[1][dt] = __builtin_amdgcn_mfma_f32_16x16x32_bf16(vf, pb[1][k2], o[1][dt], 0, 0, 0);
;                     }
;                 if (__builtin_amdgcn_ballot_w64(C[0] < -160.f && C[1] < -160.f) == ~0ull) { wdone = true;     if (lane == 0) misc[8 + wid] = 1; }
	v_mfma_f32_16x16x32_bf16 v[158:161], v[218:221], v[44:47], v[158:161]
	v_mfma_f32_16x16x32_bf16 v[94:97], v[218:221], v[48:51], v[94:97]
	ds_read_b64_tr_b16 v[218:219], v173 offset:17600
	ds_read_b64_tr_b16 v[220:221], v173 offset:18688
	s_and_b64 s[18:19], vcc, s[18:19]
	v_cndmask_b32_e64 v1, 0, 1, s[18:19]
	s_waitcnt lgkmcnt(10)
	v_mfma_f32_16x16x32_bf16 v[154:157], v[222:225], v[44:47], v[154:157]
	v_mfma_f32_16x16x32_bf16 v[90:93], v[222:225], v[48:51], v[90:93]
	ds_read_b64_tr_b16 v[222:223], v173 offset:17632
	ds_read_b64_tr_b16 v[224:225], v173 offset:18720
	v_cmp_ne_u32_e32 vcc, 0, v1
	s_cmp_eq_u64 vcc, -1
	s_cselect_b64 s[18:19], -1, 0
	s_waitcnt lgkmcnt(10)
	v_mfma_f32_16x16x32_bf16 v[150:153], v[226:229], v[44:47], v[150:153]
	v_mfma_f32_16x16x32_bf16 v[86:89], v[226:229], v[48:51], v[86:89]
	ds_read_b64_tr_b16 v[226:227], v173 offset:19584
	ds_read_b64_tr_b16 v[228:229], v173 offset:20672
	s_and_b64 s[22:23], s[20:21], s[18:19]
	s_waitcnt lgkmcnt(10)
	v_mfma_f32_16x16x32_bf16 v[146:149], v[230:233], v[44:47], v[146:149]
	v_mfma_f32_16x16x32_bf16 v[82:85], v[230:233], v[48:51], v[82:85]
	ds_read_b64_tr_b16 v[230:231], v173 offset:19616
	ds_read_b64_tr_b16 v[232:233], v173 offset:20704
	s_waitcnt lgkmcnt(10)
	v_mfma_f32_16x16x32_bf16 v[142:145], v[236:239], v[44:47], v[142:145]
	v_mfma_f32_16x16x32_bf16 v[78:81], v[236:239], v[48:51], v[78:81]
	ds_read_b64_tr_b16 v[236:237], v173 offset:19648
	ds_read_b64_tr_b16 v[238:239], v173 offset:20736
	s_waitcnt lgkmcnt(10)
	v_mfma_f32_16x16x32_bf16 v[138:141], v[240:243], v[44:47], v[138:141]
	v_mfma_f32_16x16x32_bf16 v[74:77], v[240:243], v[48:51], v[74:77]
	ds_read_b64_tr_b16 v[240:241], v173 offset:19680
	ds_read_b64_tr_b16 v[242:243], v173 offset:20768
	s_waitcnt lgkmcnt(10)
	v_mfma_f32_16x16x32_bf16 v[134:137], v[218:221], v[44:47], v[134:137]
	v_mfma_f32_16x16x32_bf16 v[70:73], v[218:221], v[48:51], v[70:73]
	ds_read_b64_tr_b16 v[218:219], v173 offset:19712
	ds_read_b64_tr_b16 v[220:221], v173 offset:20800
	s_waitcnt lgkmcnt(10)
	v_mfma_f32_16x16x32_bf16 v[114:117], v[222:225], v[44:47], v[114:117]
	v_mfma_f32_16x16x32_bf16 v[66:69], v[222:225], v[48:51], v[66:69]
	ds_read_b64_tr_b16 v[222:223], v173 offset:19744
	ds_read_b64_tr_b16 v[224:225], v173 offset:20832
	s_waitcnt lgkmcnt(10)
	v_mfma_f32_16x16x32_bf16 v[158:161], v[226:229], v[38:41], v[158:161]
	v_mfma_f32_16x16x32_bf16 v[94:97], v[226:229], v[34:37], v[94:97]
	ds_read_b64_tr_b16 v[226:227], v173 offset:19776
	ds_read_b64_tr_b16 v[228:229], v173 offset:20864
	s_waitcnt lgkmcnt(10)
	v_mfma_f32_16x16x32_bf16 v[154:157], v[230:233], v[38:41], v[154:157]
	v_mfma_f32_16x16x32_bf16 v[90:93], v[230:233], v[34:37], v[90:93]
	ds_read_b64_tr_b16 v[230:231], v173 offset:19808
	ds_read_b64_tr_b16 v[232:233], v173 offset:20896
	s_waitcnt lgkmcnt(10)
	v_mfma_f32_16x16x32_bf16 v[150:153], v[236:239], v[38:41], v[150:153]
	v_mfma_f32_16x16x32_bf16 v[86:89], v[236:239], v[34:37], v[86:89]
	s_waitcnt lgkmcnt(8)
	v_mfma_f32_16x16x32_bf16 v[146:149], v[240:243], v[38:41], v[146:149]
	v_mfma_f32_16x16x32_bf16 v[82:85], v[240:243], v[34:37], v[82:85]
	s_waitcnt lgkmcnt(6)
	v_mfma_f32_16x16x32_bf16 v[142:145], v[218:221], v[38:41], v[142:145]
	v_mfma_f32_16x16x32_bf16 v[78:81], v[218:221], v[34:37], v[78:81]
	s_waitcnt lgkmcnt(4)
	v_mfma_f32_16x16x32_bf16 v[138:141], v[222:225], v[38:41], v[138:141]
	v_mfma_f32_16x16x32_bf16 v[74:77], v[222:225], v[34:37], v[74:77]
	s_waitcnt lgkmcnt(2)
	v_mfma_f32_16x16x32_bf16 v[134:137], v[226:229], v[38:41], v[134:137]
	v_mfma_f32_16x16x32_bf16 v[70:73], v[226:229], v[34:37], v[70:73]
	s_waitcnt lgkmcnt(0)
	v_mfma_f32_16x16x32_bf16 v[114:117], v[230:233], v[38:41], v[114:117]
	v_mfma_f32_16x16x32_bf16 v[66:69], v[230:233], v[34:37], v[66:69]
	s_and_saveexec_b64 s[20:21], s[22:23]
	s_cbranch_execz .LBB0_678
	v_readlane_b32 s22, v234, 45
	s_or_b64 s[18:19], s[18:19], exec
	s_nop 0
	v_mov_b32_e32 v1, s22
	ds_write_b32 v1, v200 offset:34848

; __device__ __forceinline__ unsigned cvt_pk_bf16(float lo, float hi) { unsigned r; asm volatile("v_cvt_pk_bf16_f32 %0, %1, %2" : "=v"(r) : "v"(lo), "v"(hi)); return r; }
; __device__ __forceinline__ void st_wt8(void* ptr, u32x2 v) { asm volatile("global_store_dwordx2 %0, %1, off sc1" :: "v"(ptr), "v"(v) : "memory"); }
; __device__ __forceinline__ float bf_lo(unsigned w) { return __uint_as_float(w << 16); }
; __device__ __forceinline__ float bf_hi(unsigned w) { return __uint_as_float(w & 0xffff0000u); }
; __device__ __forceinline__ void attn_phase(const Params& p, LAS unsigned char* lds, int cidx) {
;     ...
;         if (active) {
; #pragma unroll
;             for (int mt = 0; mt < 2; ++mt)
; #pragma unroll
;                 for (int dt = 0; dt < 8; ++dt) {
;                     const size_t off = (size_t)(qrow0 + 16 * mt + fr) * DM + h * 128 + 16 * dt + 4 * fq;
;                     const u32x2 zr = __builtin_nontemporal_load((const u32x2*)(sz1 + off)); const f32x4 a = o[mt][dt];
;                     u32x2 w; w.x = cvt_pk_bf16(a[0] * bf_lo(zr.x), a[1] * bf_hi(zr.x)); w.y = cvt_pk_bf16(a[2] * bf_lo(zr.y), a[3] * bf_hi(zr.y));
;                     st_wt8(y1 + off, w);
;                 }
;         }
.LBB0_683:
	s_or_b64 exec, exec, s[2:3]
	v_readlane_b32 s2, v234, 58
	v_readlane_b32 s3, v234, 59
	s_andn2_b64 vcc, exec, s[2:3]
	s_cbranch_vccnz .LBB0_685
	v_or_b32_e32 v1, s15, v199
	v_lshlrev_b32_e32 v1, 1, v1
	v_or_b32_e32 v176, v176, v1
	v_lshl_add_u64 v[34:35], s[92:93], 0, v[176:177]
	v_readlane_b32 s2, v234, 25
	v_mov_b32_e32 v37, v177
	v_readlane_b32 s3, v234, 26
	v_or_b32_e32 v36, 32, v176
	v_lshl_add_u64 v[36:37], s[92:93], 0, v[36:37]
	v_lshl_add_u64 v[38:39], s[2:3], 0, v[176:177]
	s_mov_b64 s[6:7], 0x60
	s_mov_b64 s[14:15], 0x80
	s_mov_b64 s[18:19], 0xa0
	s_mov_b64 s[20:21], 0xc0
	v_or_b32_e32 v174, v174, v1
	v_lshl_add_u64 v[190:191], s[92:93], 0, v[176:177]
	v_lshl_add_u64 v[188:189], s[92:93], 0, v[174:175]
	global_load_dwordx2 v[204:205], v[190:191], off nt
	global_load_dwordx2 v[206:207], v[190:191], off offset:32 nt
	global_load_dwordx2 v[208:209], v[190:191], off offset:64 nt
	global_load_dwordx2 v[210:211], v[190:191], off offset:96 nt
	global_load_dwordx2 v[212:213], v[190:191], off offset:128 nt
	global_load_dwordx2 v[214:215], v[190:191], off offset:160 nt
	global_load_dwordx2 v[216:217], v[190:191], off offset:192 nt
	global_load_dwordx2 v[218:219], v[190:191], off offset:224 nt
	global_load_dwordx2 v[220:221], v[188:189], off nt
	global_load_dwordx2 v[222:223], v[188:189], off offset:32 nt
	global_load_dwordx2 v[224:225], v[188:189], off offset:64 nt
	global_load_dwordx2 v[226:227], v[188:189], off offset:96 nt
	global_load_dwordx2 v[228:229], v[188:189], off offset:128 nt
	global_load_dwordx2 v[230:231], v[188:189], off offset:160 nt
	global_load_dwordx2 v[232:233], v[188:189], off offset:192 nt
	global_load_dwordx2 v[192:193], v[188:189], off offset:224 nt
	s_mov_b64 s[22:23], 0xe0
	s_waitcnt vmcnt(0)
	v_mov_b32_e32 v34, v204
	v_mov_b32_e32 v35, v205
	v_lshlrev_b32_e32 v40, 16, v34
	v_and_b32_e32 v34, 0xffff0000, v34
	v_lshlrev_b32_e32 v41, 16, v35
	v_and_b32_e32 v35, 0xffff0000, v35
	v_mul_f32_e32 v34, v159, v34
	v_mul_f32_e32 v35, v161, v35
	v_mul_f32_e32 v40, v158, v40
	v_mul_f32_e32 v41, v160, v41
	v_cvt_pk_bf16_f32 v34, v40, v34
	v_cvt_pk_bf16_f32 v35, v41, v35
	v_lshl_add_u64 v[40:41], v[38:39], 0, 32
	global_store_dwordx2 v[38:39], v[34:35], off sc1
	v_mov_b32_e32 v34, v206
	v_mov_b32_e32 v35, v207
	v_mov_b32_e32 v37, v177
	v_or_b32_e32 v36, 64, v176
	v_lshl_add_u64 v[36:37], s[92:93], 0, v[36:37]
	v_lshlrev_b32_e32 v42, 16, v34
	v_and_b32_e32 v34, 0xffff0000, v34
	v_lshlrev_b32_e32 v43, 16, v35
	v_and_b32_e32 v35, 0xffff0000, v35
	v_mul_f32_e32 v34, v155, v34
	v_mul_f32_e32 v35, v157, v35
	v_mul_f32_e32 v42, v154, v42
	v_mul_f32_e32 v43, v156, v43
	v_cvt_pk_bf16_f32 v34, v42, v34
	v_cvt_pk_bf16_f32 v35, v43, v35
	s_nop 0
	global_store_dwordx2 v[40:41], v[34:35], off sc1
	v_mov_b32_e32 v34, v208
	v_mov_b32_e32 v35, v209
	v_mov_b32_e32 v37, v177
	v_or_b32_e32 v36, 0x60, v176
	v_lshl_add_u64 v[40:41], v[38:39], 0, 64
	v_lshl_add_u64 v[36:37], s[92:93], 0, v[36:37]
	v_lshlrev_b32_e32 v42, 16, v34
	v_and_b32_e32 v34, 0xffff0000, v34
	v_lshlrev_b32_e32 v43, 16, v35
	v_and_b32_e32 v35, 0xffff0000, v35
	v_mul_f32_e32 v34, v151, v34
	v_mul_f32_e32 v35, v153, v35
	v_mul_f32_e32 v42, v150, v42
	v_mul_f32_e32 v43, v152, v43
	v_cvt_pk_bf16_f32 v34, v42, v34
	v_cvt_pk_bf16_f32 v35, v43, v35
	s_nop 0
	global_store_dwordx2 v[40:41], v[34:35], off sc1
	v_mov_b32_e32 v34, v210
	v_mov_b32_e32 v35, v211
	v_mov_b32_e32 v37, v177
	v_or_b32_e32 v36, 0x80, v176
	v_lshl_add_u64 v[40:41], v[38:39], 0, s[6:7]
	v_lshl_add_u64 v[36:37], s[92:93], 0, v[36:37]
	v_lshlrev_b32_e32 v42, 16, v34
	v_and_b32_e32 v34, 0xffff0000, v34
	v_lshlrev_b32_e32 v43, 16, v35
	v_and_b32_e32 v35, 0xffff0000, v35
	v_mul_f32_e32 v34, v147, v34
	v_mul_f32_e32 v35, v149, v35
	v_mul_f32_e32 v42, v146, v42
	v_mul_f32_e32 v43, v148, v43
	v_cvt_pk_bf16_f32 v34, v42, v34
	v_cvt_pk_bf16_f32 v35, v43, v35
	s_nop 0
	global_store_dwordx2 v[40:41], v[34:35], off sc1
	v_mov_b32_e32 v34, v212
	v_mov_b32_e32 v35, v213
	v_mov_b32_e32 v37, v177
	v_or_b32_e32 v36, 0xa0, v176
	v_lshl_add_u64 v[40:41], v[38:39], 0, s[14:15]
	v_lshl_add_u64 v[36:37], s[92:93], 0, v[36:37]
	v_lshlrev_b32_e32 v42, 16, v34
	v_and_b32_e32 v34, 0xffff0000, v34
	v_lshlrev_b32_e32 v43, 16, v35
	v_and_b32_e32 v35, 0xffff0000, v35
	v_mul_f32_e32 v34, v143, v34
	v_mul_f32_e32 v35, v145, v35
	v_mul_f32_e32 v42, v142, v42
	v_mul_f32_e32 v43, v144, v43
	v_cvt_pk_bf16_f32 v34, v42, v34
	v_cvt_pk_bf16_f32 v35, v43, v35
	s_nop 0
	global_store_dwordx2 v[40:41], v[34:35], off sc1
	v_mov_b32_e32 v34, v214
	v_mov_b32_e32 v35, v215
	v_mov_b32_e32 v37, v177
	v_or_b32_e32 v36, 0xc0, v176
	v_lshl_add_u64 v[40:41], v[38:39], 0, s[18:19]
	v_lshl_add_u64 v[36:37], s[92:93], 0, v[36:37]
	v_or_b32_e32 v176, 0xe0, v176
	v_lshlrev_b32_e32 v42, 16, v34
	v_and_b32_e32 v34, 0xffff0000, v34
	v_lshlrev_b32_e32 v43, 16, v35
	v_and_b32_e32 v35, 0xffff0000, v35
	v_mul_f32_e32 v34, v139, v34
	v_mul_f32_e32 v35, v141, v35
	v_mul_f32_e32 v42, v138, v42
	v_mul_f32_e32 v43, v140, v43
	v_cvt_pk_bf16_f32 v34, v42, v34
	v_cvt_pk_bf16_f32 v35, v43, v35
	s_nop 0
	global_store_dwordx2 v[40:41], v[34:35], off sc1
	v_mov_b32_e32 v34, v216
	v_mov_b32_e32 v35, v217
	v_lshl_add_u64 v[36:37], v[38:39], 0, s[20:21]
	v_lshl_add_u64 v[40:41], s[92:93], 0, v[176:177]
	v_lshl_add_u64 v[38:39], v[38:39], 0, s[22:23]
; __device__ __forceinline__ unsigned cvt_pk_bf16(float lo, float hi) { unsigned r; asm volatile("v_cvt_pk_bf16_f32 %0, %1, %2" : "=v"(r) : "v"(lo), "v"(hi)); return r; }
; __device__ __forceinline__ void st_wt8(void* ptr, u32x2 v) { asm volatile("global_store_dwordx2 %0, %1, off sc1" :: "v"(ptr), "v"(v) : "memory"); }
; __device__ __forceinline__ float bf_lo(unsigned w) { return __uint_as_float(w << 16); }
; __device__ __forceinline__ float bf_hi(unsigned w) { return __uint_as_float(w & 0xffff0000u); }
; __device__ __forceinline__ void attn_phase(const Params& p, LAS unsigned char* lds, int cidx) {
;     ...
;         if (active) {
; #pragma unroll
;             for (int mt = 0; mt < 2; ++mt)
; #pragma unroll
;                 for (int dt = 0; dt < 8; ++dt) {
;                     const size_t off = (size_t)(qrow0 + 16 * mt + fr) * DM + h * 128 + 16 * dt + 4 * fq;
;                     const u32x2 zr = __builtin_nontemporal_load((const u32x2*)(sz1 + off)); const f32x4 a = o[mt][dt];
;                     u32x2 w; w.x = cvt_pk_bf16(a[0] * bf_lo(zr.x), a[1] * bf_hi(zr.x)); w.y = cvt_pk_bf16(a[2] * bf_lo(zr.y), a[3] * bf_hi(zr.y));
;                     st_wt8(y1 + off, w);
;                 }
;         }
	v_lshlrev_b32_e32 v42, 16, v34
	v_and_b32_e32 v34, 0xffff0000, v34
	v_lshlrev_b32_e32 v43, 16, v35
	v_and_b32_e32 v35, 0xffff0000, v35
	v_mul_f32_e32 v34, v135, v34
	v_mul_f32_e32 v35, v137, v35
	v_mul_f32_e32 v42, v134, v42
	v_mul_f32_e32 v43, v136, v43
	v_cvt_pk_bf16_f32 v34, v42, v34
	v_cvt_pk_bf16_f32 v35, v43, v35
	s_nop 0
	global_store_dwordx2 v[36:37], v[34:35], off sc1
	v_mov_b32_e32 v34, v218
	v_mov_b32_e32 v35, v219
	v_lshl_add_u64 v[36:37], s[92:93], 0, v[174:175]
	v_lshlrev_b32_e32 v1, 16, v34
	v_and_b32_e32 v34, 0xffff0000, v34
	v_lshlrev_b32_e32 v40, 16, v35
	v_and_b32_e32 v35, 0xffff0000, v35
	v_mul_f32_e32 v34, v115, v34
	v_mul_f32_e32 v35, v117, v35
	v_mul_f32_e32 v1, v114, v1
	v_mul_f32_e32 v40, v116, v40
	v_cvt_pk_bf16_f32 v34, v1, v34
	v_cvt_pk_bf16_f32 v35, v40, v35
	s_nop 0
	global_store_dwordx2 v[38:39], v[34:35], off sc1
	v_mov_b32_e32 v34, v220
	v_mov_b32_e32 v35, v221
	v_mov_b32_e32 v37, v175
	v_or_b32_e32 v36, 32, v174
	v_lshl_add_u64 v[38:39], s[2:3], 0, v[174:175]
	v_lshl_add_u64 v[36:37], s[92:93], 0, v[36:37]
	v_lshlrev_b32_e32 v1, 16, v34
	v_and_b32_e32 v34, 0xffff0000, v34
	v_lshlrev_b32_e32 v40, 16, v35
	v_and_b32_e32 v35, 0xffff0000, v35
	v_mul_f32_e32 v34, v95, v34
	v_mul_f32_e32 v35, v97, v35
	v_mul_f32_e32 v1, v94, v1
	v_mul_f32_e32 v40, v96, v40
	v_cvt_pk_bf16_f32 v34, v1, v34
	v_cvt_pk_bf16_f32 v35, v40, v35
	v_lshl_add_u64 v[40:41], v[38:39], 0, 32
	global_store_dwordx2 v[38:39], v[34:35], off sc1
	v_mov_b32_e32 v34, v222
	v_mov_b32_e32 v35, v223
	v_mov_b32_e32 v37, v175
	v_or_b32_e32 v36, 64, v174
	v_lshl_add_u64 v[36:37], s[92:93], 0, v[36:37]
	v_lshlrev_b32_e32 v1, 16, v34
	v_and_b32_e32 v34, 0xffff0000, v34
	v_lshlrev_b32_e32 v42, 16, v35
	v_and_b32_e32 v35, 0xffff0000, v35
	v_mul_f32_e32 v34, v91, v34
	v_mul_f32_e32 v35, v93, v35
	v_mul_f32_e32 v1, v90, v1
	v_mul_f32_e32 v42, v92, v42
	v_cvt_pk_bf16_f32 v34, v1, v34
	v_cvt_pk_bf16_f32 v35, v42, v35
	s_nop 0
	global_store_dwordx2 v[40:41], v[34:35], off sc1
	v_mov_b32_e32 v34, v224
	v_mov_b32_e32 v35, v225
	v_mov_b32_e32 v37, v175
	v_or_b32_e32 v36, 0x60, v174
	v_lshl_add_u64 v[40:41], v[38:39], 0, 64
	v_lshl_add_u64 v[36:37], s[92:93], 0, v[36:37]
	v_lshlrev_b32_e32 v1, 16, v34
	v_and_b32_e32 v34, 0xffff0000, v34
	v_lshlrev_b32_e32 v42, 16, v35
	v_and_b32_e32 v35, 0xffff0000, v35
	v_mul_f32_e32 v34, v87, v34
	v_mul_f32_e32 v35, v89, v35
	v_mul_f32_e32 v1, v86, v1
	v_mul_f32_e32 v42, v88, v42
	v_cvt_pk_bf16_f32 v34, v1, v34
	v_cvt_pk_bf16_f32 v35, v42, v35
	s_nop 0
	global_store_dwordx2 v[40:41], v[34:35], off sc1
	v_mov_b32_e32 v34, v226
	v_mov_b32_e32 v35, v227
	v_mov_b32_e32 v37, v175
	v_or_b32_e32 v36, 0x80, v174
	v_lshl_add_u64 v[40:41], v[38:39], 0, s[6:7]
	v_lshl_add_u64 v[36:37], s[92:93], 0, v[36:37]
	v_lshlrev_b32_e32 v1, 16, v34
	v_and_b32_e32 v34, 0xffff0000, v34
	v_lshlrev_b32_e32 v42, 16, v35
	v_and_b32_e32 v35, 0xffff0000, v35
	v_mul_f32_e32 v34, v83, v34
	v_mul_f32_e32 v35, v85, v35
	v_mul_f32_e32 v1, v82, v1
	v_mul_f32_e32 v42, v84, v42
	v_cvt_pk_bf16_f32 v34, v1, v34
	v_cvt_pk_bf16_f32 v35, v42, v35
	s_nop 0
	global_store_dwordx2 v[40:41], v[34:35], off sc1
	v_mov_b32_e32 v34, v228
	v_mov_b32_e32 v35, v229
	v_mov_b32_e32 v37, v175
	v_or_b32_e32 v36, 0xa0, v174
	v_lshl_add_u64 v[40:41], v[38:39], 0, s[14:15]
	v_lshl_add_u64 v[36:37], s[92:93], 0, v[36:37]
	v_lshlrev_b32_e32 v1, 16, v34
	v_and_b32_e32 v34, 0xffff0000, v34
	v_lshlrev_b32_e32 v42, 16, v35
	v_and_b32_e32 v35, 0xffff0000, v35
	v_mul_f32_e32 v34, v79, v34
	v_mul_f32_e32 v35, v81, v35
	v_mul_f32_e32 v1, v78, v1
	v_mul_f32_e32 v42, v80, v42
	v_cvt_pk_bf16_f32 v34, v1, v34
	v_cvt_pk_bf16_f32 v35, v42, v35
	s_nop 0
	global_store_dwordx2 v[40:41], v[34:35], off sc1
	v_mov_b32_e32 v34, v230
	v_mov_b32_e32 v35, v231
	v_mov_b32_e32 v37, v175
	v_or_b32_e32 v36, 0xc0, v174
	v_lshl_add_u64 v[40:41], v[38:39], 0, s[18:19]
	v_lshl_add_u64 v[36:37], s[92:93], 0, v[36:37]
	v_or_b32_e32 v174, 0xe0, v174
	v_lshlrev_b32_e32 v1, 16, v34
	v_and_b32_e32 v34, 0xffff0000, v34
	v_lshlrev_b32_e32 v42, 16, v35
	v_and_b32_e32 v35, 0xffff0000, v35
	v_mul_f32_e32 v34, v75, v34
	v_mul_f32_e32 v35, v77, v35
	v_mul_f32_e32 v1, v74, v1
	v_mul_f32_e32 v42, v76, v42
	v_cvt_pk_bf16_f32 v34, v1, v34
	v_cvt_pk_bf16_f32 v35, v42, v35
	s_nop 0
	global_store_dwordx2 v[40:41], v[34:35], off sc1
	v_mov_b32_e32 v34, v232
	v_mov_b32_e32 v35, v233
	v_lshl_add_u64 v[36:37], v[38:39], 0, s[20:21]
	v_lshl_add_u64 v[40:41], s[92:93], 0, v[174:175]
	v_lshlrev_b32_e32 v1, 16, v34
	v_and_b32_e32 v34, 0xffff0000, v34
	v_lshlrev_b32_e32 v42, 16, v35
	v_and_b32_e32 v35, 0xffff0000, v35
	v_mul_f32_e32 v34, v71, v34
	v_mul_f32_e32 v35, v73, v35
	v_mul_f32_e32 v1, v70, v1
	v_mul_f32_e32 v42, v72, v42
	v_cvt_pk_bf16_f32 v34, v1, v34
	v_cvt_pk_bf16_f32 v35, v42, v35
	s_nop 0
	global_store_dwordx2 v[36:37], v[34:35], off sc1
	v_mov_b32_e32 v34, v192
	v_mov_b32_e32 v35, v193
	v_lshlrev_b32_e32 v1, 16, v34
	v_and_b32_e32 v34, 0xffff0000, v34
	v_lshlrev_b32_e32 v36, 16, v35
	v_and_b32_e32 v35, 0xffff0000, v35
	v_mul_f32_e32 v34, v67, v34
	v_mul_f32_e32 v36, v68, v36
	v_mul_f32_e32 v35, v69, v35
	v_mul_f32_e32 v1, v66, v1
	v_cvt_pk_bf16_f32 v34, v1, v34
	v_cvt_pk_bf16_f32 v35, v36, v35
	v_lshl_add_u64 v[36:37], v[38:39], 0, s[22:23]
	global_store_dwordx2 v[36:37], v[34:35], off sc1
